# FFN-up epilogue reads next tile's row sums and conv weights from LDS slots prefetched by LDS-DMA in the previous epilogue (static LDS 8192)
# baseline (speedup 1.0000x reference)
.Lst_out_s3:
	s_lshl_b32 s8, s0, 8
	s_add_i32 s8, s8, s56
	s_lshl_b32 s9, s1, 7
	s_add_i32 s9, s9, s49
	s_lshl_b32 s10, s0, 3
	s_lshr_b32 s11, s56, 5
	s_add_i32 s10, s10, s11
	v_add_u32_e32 v200, s8, v163
	v_lshlrev_b32_e32 v213, 2, v200
	v_lshrrev_b32_e32 v212, 6, v222
	v_lshlrev_b32_e32 v109, 10, v212
	v_lshl_add_u32 v109, v225, 5, v109
	v_add_u32_e32 v109, 0x21040, v109
	v_lshlrev_b32_e32 v212, 9, v212
	v_lshl_add_u32 v212, v163, 2, v212
	v_add_u32_e32 v212, 0x20040, v212
	s_cmp_eq_u32 s48, 1
	s_cbranch_scc0 .Lfs3_ready
	v_lshl_add_u32 v201, v225, 3, s9
	v_lshlrev_b32_e32 v215, 2, v201
	global_load_dword v188, v213, s[12:13]
	global_load_dword v189, v213, s[12:13] offset:64
	global_load_dword v190, v213, s[12:13] offset:128
	global_load_dword v191, v213, s[12:13] offset:192
	global_load_dword v192, v213, s[12:13] offset:256
	global_load_dword v193, v213, s[12:13] offset:320
	global_load_dword v194, v213, s[12:13] offset:384
	global_load_dword v195, v213, s[12:13] offset:448
	global_load_dwordx4 v[76:79], v215, s[82:83]
	v_add_u32_e32 v217, 0xb000, v215
	global_load_dwordx4 v[80:83], v217, s[82:83]
	v_add_u32_e32 v217, 0x16000, v215
	global_load_dwordx4 v[84:87], v217, s[82:83]
	global_load_dwordx4 v[88:91], v215, s[84:85]
	v_add_u32_e32 v217, 0x5800, v215
	global_load_dwordx4 v[92:95], v217, s[82:83]
	v_add_u32_e32 v217, 0x10800, v215
	global_load_dwordx4 v[96:99], v217, s[82:83]
	v_add_u32_e32 v217, 0x1b800, v215
	global_load_dwordx4 v[100:103], v217, s[82:83]
	v_add_u32_e32 v217, 0x5800, v215
	global_load_dwordx4 v[104:107], v217, s[84:85]
	s_waitcnt vmcnt(8)
	ds_write_b32 v212, v188
	ds_write_b32 v212, v189 offset:64
	ds_write_b32 v212, v190 offset:128
	ds_write_b32 v212, v191 offset:192
	ds_write_b32 v212, v192 offset:256
	ds_write_b32 v212, v193 offset:320
	ds_write_b32 v212, v194 offset:384
	ds_write_b32 v212, v195 offset:448
	s_waitcnt vmcnt(0)
	ds_write_b128 v109, v[76:79]
	ds_write_b128 v109, v[80:83] offset:128
	ds_write_b128 v109, v[84:87] offset:256
	ds_write_b128 v109, v[88:91] offset:384
	ds_write_b128 v109, v[92:95] offset:512
	ds_write_b128 v109, v[96:99] offset:640
	ds_write_b128 v109, v[100:103] offset:768
	ds_write_b128 v109, v[104:107] offset:896
	s_waitcnt lgkmcnt(0)
	global_load_dwordx4 v[76:79], v215, s[82:83] offset:16
	v_add_u32_e32 v217, 0xb000, v215
	global_load_dwordx4 v[80:83], v217, s[82:83] offset:16
	v_add_u32_e32 v217, 0x16000, v215
	global_load_dwordx4 v[84:87], v217, s[82:83] offset:16
	global_load_dwordx4 v[88:91], v215, s[84:85] offset:16
	v_add_u32_e32 v217, 0x5800, v215
	global_load_dwordx4 v[92:95], v217, s[82:83] offset:16
	v_add_u32_e32 v217, 0x10800, v215
	global_load_dwordx4 v[96:99], v217, s[82:83] offset:16
	v_add_u32_e32 v217, 0x1b800, v215
	global_load_dwordx4 v[100:103], v217, s[82:83] offset:16
	v_add_u32_e32 v217, 0x5800, v215
	global_load_dwordx4 v[104:107], v217, s[84:85] offset:16
	s_waitcnt vmcnt(0)
	ds_write_b128 v109, v[76:79] offset:16
	ds_write_b128 v109, v[80:83] offset:144
	ds_write_b128 v109, v[84:87] offset:272
	ds_write_b128 v109, v[88:91] offset:400
	ds_write_b128 v109, v[92:95] offset:528
	ds_write_b128 v109, v[96:99] offset:656
	ds_write_b128 v109, v[100:103] offset:784
	ds_write_b128 v109, v[104:107] offset:912
	s_waitcnt lgkmcnt(0)
.Lfs3_ready:
	ds_read_b32 v188, v212
	ds_read_b32 v189, v212 offset:64
	ds_read_b32 v190, v212 offset:128
	ds_read_b32 v191, v212 offset:192
	ds_read_b32 v192, v212 offset:256
	ds_read_b32 v193, v212 offset:320
	ds_read_b32 v194, v212 offset:384
	ds_read_b32 v195, v212 offset:448
	ds_read_b128 v[76:79], v109
	ds_read_b128 v[80:83], v109 offset:128
	ds_read_b128 v[84:87], v109 offset:256
	ds_read_b128 v[88:91], v109 offset:384
	ds_read_b128 v[92:95], v109 offset:512
	ds_read_b128 v[96:99], v109 offset:640
	ds_read_b128 v[100:103], v109 offset:768
	ds_read_b128 v[104:107], v109 offset:896
	v_lshl_add_u32 v201, v225, 3, s9
	v_lshlrev_b32_e32 v212, 2, v201
	v_mul_u32_u24_e32 v215, 0x2c00, v200
	v_lshl_add_u32 v215, v201, 1, v215
	v_add_u32_e32 v213, s10, v163
	v_mul_u32_u24_e32 v217, 0xb000, v213
	v_add_u32_e32 v217, v217, v212
	v_cmp_gt_u32_e64 s[8:9], 2, v163
	v_cmp_lt_u32_e64 s[10:11], 13, v163
	v_cmp_lt_u32_e32 vcc, 1, v163
	v_mov_b32_e32 v214, 1.0
	v_mov_b32_e32 v216, 0xbfb8aa3b
	v_mov_b32_e32 v108, 0x3727c5ac
	s_waitcnt lgkmcnt(8)
	v_fmamk_f32 v188, v188, 0x3a000000, v108
	v_fmamk_f32 v189, v189, 0x3a000000, v108
	v_fmamk_f32 v190, v190, 0x3a000000, v108
	v_fmamk_f32 v191, v191, 0x3a000000, v108
	v_fmamk_f32 v192, v192, 0x3a000000, v108
	v_fmamk_f32 v193, v193, 0x3a000000, v108
	v_fmamk_f32 v194, v194, 0x3a000000, v108
	v_fmamk_f32 v195, v195, 0x3a000000, v108
	v_rsq_f32_e32 v188, v188
	v_rsq_f32_e32 v189, v189
	v_rsq_f32_e32 v190, v190
	v_rsq_f32_e32 v191, v191
	v_rsq_f32_e32 v192, v192
	v_rsq_f32_e32 v193, v193
	v_rsq_f32_e32 v194, v194
	v_rsq_f32_e32 v195, v195
	v_pk_mul_f32 v[158:159], v[158:159], v[188:189] op_sel_hi:[1,0]
	v_pk_mul_f32 v[160:161], v[160:161], v[188:189] op_sel_hi:[1,0]
	v_pk_mul_f32 v[60:61], v[60:61], v[188:189] op_sel_hi:[1,0]
	v_pk_mul_f32 v[62:63], v[62:63], v[188:189] op_sel_hi:[1,0]
	v_pk_mul_f32 v[154:155], v[154:155], v[188:189] op_sel_hi:[1,0]
	v_pk_mul_f32 v[156:157], v[156:157], v[188:189] op_sel_hi:[1,0]
	v_pk_mul_f32 v[56:57], v[56:57], v[188:189] op_sel_hi:[1,0]
	v_pk_mul_f32 v[58:59], v[58:59], v[188:189] op_sel_hi:[1,0]
	v_pk_mul_f32 v[150:151], v[150:151], v[188:189] op_sel:[0,1] op_sel_hi:[1,1]
	v_pk_mul_f32 v[152:153], v[152:153], v[188:189] op_sel:[0,1] op_sel_hi:[1,1]
	v_pk_mul_f32 v[52:53], v[52:53], v[188:189] op_sel:[0,1] op_sel_hi:[1,1]
	v_pk_mul_f32 v[54:55], v[54:55], v[188:189] op_sel:[0,1] op_sel_hi:[1,1]
	v_pk_mul_f32 v[142:143], v[142:143], v[188:189] op_sel:[0,1] op_sel_hi:[1,1]
	v_pk_mul_f32 v[144:145], v[144:145], v[188:189] op_sel:[0,1] op_sel_hi:[1,1]
	v_pk_mul_f32 v[44:45], v[44:45], v[188:189] op_sel:[0,1] op_sel_hi:[1,1]
	v_pk_mul_f32 v[46:47], v[46:47], v[188:189] op_sel:[0,1] op_sel_hi:[1,1]
	v_pk_mul_f32 v[146:147], v[146:147], v[190:191] op_sel_hi:[1,0]
	v_pk_mul_f32 v[148:149], v[148:149], v[190:191] op_sel_hi:[1,0]
	v_pk_mul_f32 v[48:49], v[48:49], v[190:191] op_sel_hi:[1,0]
	v_pk_mul_f32 v[50:51], v[50:51], v[190:191] op_sel_hi:[1,0]
	v_pk_mul_f32 v[134:135], v[134:135], v[190:191] op_sel_hi:[1,0]
	v_pk_mul_f32 v[136:137], v[136:137], v[190:191] op_sel_hi:[1,0]
	v_pk_mul_f32 v[36:37], v[36:37], v[190:191] op_sel_hi:[1,0]
	v_pk_mul_f32 v[38:39], v[38:39], v[190:191] op_sel_hi:[1,0]
	v_pk_mul_f32 v[138:139], v[138:139], v[190:191] op_sel:[0,1] op_sel_hi:[1,1]
	v_pk_mul_f32 v[140:141], v[140:141], v[190:191] op_sel:[0,1] op_sel_hi:[1,1]
	v_pk_mul_f32 v[40:41], v[40:41], v[190:191] op_sel:[0,1] op_sel_hi:[1,1]
	v_pk_mul_f32 v[42:43], v[42:43], v[190:191] op_sel:[0,1] op_sel_hi:[1,1]
	v_pk_mul_f32 v[130:131], v[130:131], v[190:191] op_sel:[0,1] op_sel_hi:[1,1]
	v_pk_mul_f32 v[132:133], v[132:133], v[190:191] op_sel:[0,1] op_sel_hi:[1,1]
	v_pk_mul_f32 v[32:33], v[32:33], v[190:191] op_sel:[0,1] op_sel_hi:[1,1]
	v_pk_mul_f32 v[34:35], v[34:35], v[190:191] op_sel:[0,1] op_sel_hi:[1,1]
	v_pk_mul_f32 v[126:127], v[126:127], v[192:193] op_sel_hi:[1,0]
	v_pk_mul_f32 v[128:129], v[128:129], v[192:193] op_sel_hi:[1,0]
	v_pk_mul_f32 v[28:29], v[28:29], v[192:193] op_sel_hi:[1,0]
	v_pk_mul_f32 v[30:31], v[30:31], v[192:193] op_sel_hi:[1,0]
	v_pk_mul_f32 v[118:119], v[118:119], v[192:193] op_sel_hi:[1,0]
	v_pk_mul_f32 v[120:121], v[120:121], v[192:193] op_sel_hi:[1,0]
	v_pk_mul_f32 v[16:17], v[16:17], v[192:193] op_sel_hi:[1,0]
	v_pk_mul_f32 v[18:19], v[18:19], v[192:193] op_sel_hi:[1,0]
	v_pk_mul_f32 v[122:123], v[122:123], v[192:193] op_sel:[0,1] op_sel_hi:[1,1]
	v_pk_mul_f32 v[124:125], v[124:125], v[192:193] op_sel:[0,1] op_sel_hi:[1,1]
	v_pk_mul_f32 v[24:25], v[24:25], v[192:193] op_sel:[0,1] op_sel_hi:[1,1]
	v_pk_mul_f32 v[26:27], v[26:27], v[192:193] op_sel:[0,1] op_sel_hi:[1,1]
	v_pk_mul_f32 v[110:111], v[110:111], v[192:193] op_sel:[0,1] op_sel_hi:[1,1]
	v_pk_mul_f32 v[112:113], v[112:113], v[192:193] op_sel:[0,1] op_sel_hi:[1,1]
	v_pk_mul_f32 v[12:13], v[12:13], v[192:193] op_sel:[0,1] op_sel_hi:[1,1]
	v_pk_mul_f32 v[14:15], v[14:15], v[192:193] op_sel:[0,1] op_sel_hi:[1,1]
	v_pk_mul_f32 v[114:115], v[114:115], v[194:195] op_sel_hi:[1,0]
	v_pk_mul_f32 v[116:117], v[116:117], v[194:195] op_sel_hi:[1,0]
	v_pk_mul_f32 v[20:21], v[20:21], v[194:195] op_sel_hi:[1,0]
	v_pk_mul_f32 v[22:23], v[22:23], v[194:195] op_sel_hi:[1,0]
	v_pk_mul_f32 v[68:69], v[68:69], v[194:195] op_sel_hi:[1,0]
	v_pk_mul_f32 v[70:71], v[70:71], v[194:195] op_sel_hi:[1,0]
	v_pk_mul_f32 v[8:9], v[8:9], v[194:195] op_sel_hi:[1,0]
	v_pk_mul_f32 v[10:11], v[10:11], v[194:195] op_sel_hi:[1,0]
	v_pk_mul_f32 v[72:73], v[72:73], v[194:195] op_sel:[0,1] op_sel_hi:[1,1]
	v_pk_mul_f32 v[74:75], v[74:75], v[194:195] op_sel:[0,1] op_sel_hi:[1,1]
	v_pk_mul_f32 v[4:5], v[4:5], v[194:195] op_sel:[0,1] op_sel_hi:[1,1]
	v_pk_mul_f32 v[6:7], v[6:7], v[194:195] op_sel:[0,1] op_sel_hi:[1,1]
	v_pk_mul_f32 v[64:65], v[64:65], v[194:195] op_sel:[0,1] op_sel_hi:[1,1]
	v_pk_mul_f32 v[66:67], v[66:67], v[194:195] op_sel:[0,1] op_sel_hi:[1,1]
	v_pk_mul_f32 v[0:1], v[0:1], v[194:195] op_sel:[0,1] op_sel_hi:[1,1]
	v_pk_mul_f32 v[2:3], v[2:3], v[194:195] op_sel:[0,1] op_sel_hi:[1,1]
	s_nop 1
	s_mov_b64 exec, s[8:9]
	v_add_u32_e32 v213, 0x5800, v217
	global_store_dwordx4 v217, v[158:161], s[70:71]
	global_store_dwordx4 v213, v[154:157], s[70:71]
	global_store_dwordx4 v217, v[60:63], s[70:71] offset:16
	global_store_dwordx4 v213, v[56:59], s[70:71] offset:16
	s_mov_b64 exec, s[10:11]
	v_add_u32_e32 v213, 0xfff7c000, v217
	global_store_dwordx4 v213, v[72:75], s[70:71]
	global_store_dwordx4 v213, v[4:7], s[70:71] offset:16
	v_add_u32_e32 v213, 0xfff81800, v217
	global_store_dwordx4 v213, v[64:67], s[70:71]
	global_store_dwordx4 v213, v[0:3], s[70:71] offset:16
	s_mov_b64 exec, -1
	v_cmp_eq_u32_e64 s[8:9], 15, v163
	ds_read_b128 v[204:207], v109 offset:784
	ds_read_b128 v[208:211], v109 offset:912
	s_waitcnt lgkmcnt(0)
	v_pk_fma_f32 v[188:189], v[158:159], v[84:85], v[88:89]
	v_pk_fma_f32 v[190:191], v[160:161], v[86:87], v[90:91]
	v_pk_fma_f32 v[192:193], v[154:155], v[100:101], v[104:105]
	v_pk_fma_f32 v[194:195], v[156:157], v[102:103], v[106:107]
	v_fmac_f32_dpp v188, v158, v80 row_shr:1 row_mask:0xf bank_mask:0xf
	v_fmac_f32_dpp v189, v159, v81 row_shr:1 row_mask:0xf bank_mask:0xf
	v_fmac_f32_dpp v190, v160, v82 row_shr:1 row_mask:0xf bank_mask:0xf
	v_fmac_f32_dpp v191, v161, v83 row_shr:1 row_mask:0xf bank_mask:0xf
	v_fmac_f32_dpp v192, v154, v96 row_shr:1 row_mask:0xf bank_mask:0xf
	v_fmac_f32_dpp v193, v155, v97 row_shr:1 row_mask:0xf bank_mask:0xf
	v_fmac_f32_dpp v194, v156, v98 row_shr:1 row_mask:0xf bank_mask:0xf
	v_fmac_f32_dpp v195, v157, v99 row_shr:1 row_mask:0xf bank_mask:0xf
	v_fmac_f32_dpp v188, v158, v76 row_shr:2 row_mask:0xf bank_mask:0xf
	v_fmac_f32_dpp v189, v159, v77 row_shr:2 row_mask:0xf bank_mask:0xf
	v_fmac_f32_dpp v190, v160, v78 row_shr:2 row_mask:0xf bank_mask:0xf
	v_fmac_f32_dpp v191, v161, v79 row_shr:2 row_mask:0xf bank_mask:0xf
	v_fmac_f32_dpp v192, v154, v92 row_shr:2 row_mask:0xf bank_mask:0xf
	v_fmac_f32_dpp v193, v155, v93 row_shr:2 row_mask:0xf bank_mask:0xf
	v_fmac_f32_dpp v194, v156, v94 row_shr:2 row_mask:0xf bank_mask:0xf
	v_fmac_f32_dpp v195, v157, v95 row_shr:2 row_mask:0xf bank_mask:0xf
	v_pk_mul_f32 v[196:197], v[188:189], v[216:217] op_sel_hi:[1,0]
	v_pk_mul_f32 v[198:199], v[190:191], v[216:217] op_sel_hi:[1,0]
	v_exp_f32_e32 v196, v196
	v_exp_f32_e32 v197, v197
	v_exp_f32_e32 v198, v198
	v_exp_f32_e32 v199, v199
	v_pk_add_f32 v[196:197], v[196:197], v[214:215] op_sel_hi:[1,0]
	v_pk_add_f32 v[198:199], v[198:199], v[214:215] op_sel_hi:[1,0]
	v_rcp_f32_e32 v196, v196
	v_rcp_f32_e32 v197, v197
	v_rcp_f32_e32 v198, v198
	v_rcp_f32_e32 v199, v199
	v_pk_mul_f32 v[188:189], v[188:189], v[196:197]
	v_pk_mul_f32 v[190:191], v[190:191], v[198:199]
	v_pk_mul_f32 v[188:189], v[188:189], v[192:193]
	v_pk_mul_f32 v[190:191], v[190:191], v[194:195]
	v_cvt_pk_bf16_f32 v200, v188, v189
	v_cvt_pk_bf16_f32 v201, v190, v191
	v_pk_fma_f32 v[188:189], v[150:151], v[84:85], v[88:89]
	v_pk_fma_f32 v[190:191], v[152:153], v[86:87], v[90:91]
	v_pk_fma_f32 v[192:193], v[142:143], v[100:101], v[104:105]
	v_pk_fma_f32 v[194:195], v[144:145], v[102:103], v[106:107]
	v_cndmask_b32_e64 v158, v150, v158, s[10:11]
	v_cndmask_b32_e64 v159, v151, v159, s[10:11]
	v_cndmask_b32_e64 v160, v152, v160, s[10:11]
	v_cndmask_b32_e64 v161, v153, v161, s[10:11]
	v_cndmask_b32_e64 v154, v142, v154, s[10:11]
	v_cndmask_b32_e64 v155, v143, v155, s[10:11]
	v_cndmask_b32_e64 v156, v144, v156, s[10:11]
	v_cndmask_b32_e64 v157, v145, v157, s[10:11]
	v_fmac_f32_dpp v188, v158, v76 row_ror:2 row_mask:0xf bank_mask:0xf
	v_fmac_f32_dpp v189, v159, v77 row_ror:2 row_mask:0xf bank_mask:0xf
	v_fmac_f32_dpp v190, v160, v78 row_ror:2 row_mask:0xf bank_mask:0xf
	v_fmac_f32_dpp v191, v161, v79 row_ror:2 row_mask:0xf bank_mask:0xf
	v_fmac_f32_dpp v192, v154, v92 row_ror:2 row_mask:0xf bank_mask:0xf
	v_fmac_f32_dpp v193, v155, v93 row_ror:2 row_mask:0xf bank_mask:0xf
	v_fmac_f32_dpp v194, v156, v94 row_ror:2 row_mask:0xf bank_mask:0xf
	v_fmac_f32_dpp v195, v157, v95 row_ror:2 row_mask:0xf bank_mask:0xf
	v_cndmask_b32_e64 v158, v150, v158, s[8:9]
	v_cndmask_b32_e64 v159, v151, v159, s[8:9]
	v_cndmask_b32_e64 v160, v152, v160, s[8:9]
	v_cndmask_b32_e64 v161, v153, v161, s[8:9]
	v_cndmask_b32_e64 v154, v142, v154, s[8:9]
	v_cndmask_b32_e64 v155, v143, v155, s[8:9]
	v_cndmask_b32_e64 v156, v144, v156, s[8:9]
	v_cndmask_b32_e64 v157, v145, v157, s[8:9]
	v_fmac_f32_dpp v188, v158, v80 row_ror:1 row_mask:0xf bank_mask:0xf
	v_fmac_f32_dpp v189, v159, v81 row_ror:1 row_mask:0xf bank_mask:0xf
	v_fmac_f32_dpp v190, v160, v82 row_ror:1 row_mask:0xf bank_mask:0xf
	v_fmac_f32_dpp v191, v161, v83 row_ror:1 row_mask:0xf bank_mask:0xf
	v_fmac_f32_dpp v192, v154, v96 row_ror:1 row_mask:0xf bank_mask:0xf
	v_fmac_f32_dpp v193, v155, v97 row_ror:1 row_mask:0xf bank_mask:0xf
	v_fmac_f32_dpp v194, v156, v98 row_ror:1 row_mask:0xf bank_mask:0xf
	v_fmac_f32_dpp v195, v157, v99 row_ror:1 row_mask:0xf bank_mask:0xf
	v_pk_mul_f32 v[196:197], v[188:189], v[216:217] op_sel_hi:[1,0]
	v_pk_mul_f32 v[198:199], v[190:191], v[216:217] op_sel_hi:[1,0]
	v_exp_f32_e32 v196, v196
	v_exp_f32_e32 v197, v197
	v_exp_f32_e32 v198, v198
	v_exp_f32_e32 v199, v199
	v_pk_add_f32 v[196:197], v[196:197], v[214:215] op_sel_hi:[1,0]
	v_pk_add_f32 v[198:199], v[198:199], v[214:215] op_sel_hi:[1,0]
	v_rcp_f32_e32 v196, v196
	v_rcp_f32_e32 v197, v197
	v_rcp_f32_e32 v198, v198
	v_rcp_f32_e32 v199, v199
	v_pk_mul_f32 v[188:189], v[188:189], v[196:197]
	v_pk_mul_f32 v[190:191], v[190:191], v[198:199]
	v_pk_mul_f32 v[188:189], v[188:189], v[192:193]
	v_pk_mul_f32 v[190:191], v[190:191], v[194:195]
	v_cvt_pk_bf16_f32 v158, v188, v189
	v_cvt_pk_bf16_f32 v159, v190, v191
	ds_read_b128 v[154:157], v109 offset:16
	v_pk_fma_f32 v[188:189], v[146:147], v[84:85], v[88:89]
	v_pk_fma_f32 v[190:191], v[148:149], v[86:87], v[90:91]
	v_pk_fma_f32 v[192:193], v[134:135], v[100:101], v[104:105]
	v_pk_fma_f32 v[194:195], v[136:137], v[102:103], v[106:107]
	v_cndmask_b32_e64 v150, v146, v150, s[10:11]
	v_cndmask_b32_e64 v151, v147, v151, s[10:11]
	v_cndmask_b32_e64 v152, v148, v152, s[10:11]
	v_cndmask_b32_e64 v153, v149, v153, s[10:11]
	v_cndmask_b32_e64 v142, v134, v142, s[10:11]
	v_cndmask_b32_e64 v143, v135, v143, s[10:11]
	v_cndmask_b32_e64 v144, v136, v144, s[10:11]
	v_cndmask_b32_e64 v145, v137, v145, s[10:11]
	v_fmac_f32_dpp v188, v150, v76 row_ror:2 row_mask:0xf bank_mask:0xf
	v_fmac_f32_dpp v189, v151, v77 row_ror:2 row_mask:0xf bank_mask:0xf
	v_fmac_f32_dpp v190, v152, v78 row_ror:2 row_mask:0xf bank_mask:0xf
	v_fmac_f32_dpp v191, v153, v79 row_ror:2 row_mask:0xf bank_mask:0xf
	v_fmac_f32_dpp v192, v142, v92 row_ror:2 row_mask:0xf bank_mask:0xf
	v_fmac_f32_dpp v193, v143, v93 row_ror:2 row_mask:0xf bank_mask:0xf
	v_fmac_f32_dpp v194, v144, v94 row_ror:2 row_mask:0xf bank_mask:0xf
	v_fmac_f32_dpp v195, v145, v95 row_ror:2 row_mask:0xf bank_mask:0xf
	v_cndmask_b32_e64 v150, v146, v150, s[8:9]
	v_cndmask_b32_e64 v151, v147, v151, s[8:9]
	v_cndmask_b32_e64 v152, v148, v152, s[8:9]
	v_cndmask_b32_e64 v153, v149, v153, s[8:9]
	v_cndmask_b32_e64 v142, v134, v142, s[8:9]
	v_cndmask_b32_e64 v143, v135, v143, s[8:9]
	v_cndmask_b32_e64 v144, v136, v144, s[8:9]
	v_cndmask_b32_e64 v145, v137, v145, s[8:9]
	v_fmac_f32_dpp v188, v150, v80 row_ror:1 row_mask:0xf bank_mask:0xf
	v_fmac_f32_dpp v189, v151, v81 row_ror:1 row_mask:0xf bank_mask:0xf
	v_fmac_f32_dpp v190, v152, v82 row_ror:1 row_mask:0xf bank_mask:0xf
	v_fmac_f32_dpp v191, v153, v83 row_ror:1 row_mask:0xf bank_mask:0xf
	v_fmac_f32_dpp v192, v142, v96 row_ror:1 row_mask:0xf bank_mask:0xf
	v_fmac_f32_dpp v193, v143, v97 row_ror:1 row_mask:0xf bank_mask:0xf
	v_fmac_f32_dpp v194, v144, v98 row_ror:1 row_mask:0xf bank_mask:0xf
	v_fmac_f32_dpp v195, v145, v99 row_ror:1 row_mask:0xf bank_mask:0xf
	v_pk_mul_f32 v[196:197], v[188:189], v[216:217] op_sel_hi:[1,0]
	v_pk_mul_f32 v[198:199], v[190:191], v[216:217] op_sel_hi:[1,0]
	v_exp_f32_e32 v196, v196
	v_exp_f32_e32 v197, v197
	v_exp_f32_e32 v198, v198
	v_exp_f32_e32 v199, v199
	v_pk_add_f32 v[196:197], v[196:197], v[214:215] op_sel_hi:[1,0]
	v_pk_add_f32 v[198:199], v[198:199], v[214:215] op_sel_hi:[1,0]
	v_rcp_f32_e32 v196, v196
	v_rcp_f32_e32 v197, v197
	v_rcp_f32_e32 v198, v198
	v_rcp_f32_e32 v199, v199
	v_pk_mul_f32 v[188:189], v[188:189], v[196:197]
	v_pk_mul_f32 v[190:191], v[190:191], v[198:199]
	v_pk_mul_f32 v[188:189], v[188:189], v[192:193]
	v_pk_mul_f32 v[190:191], v[190:191], v[194:195]
	v_cvt_pk_bf16_f32 v150, v188, v189
	v_cvt_pk_bf16_f32 v151, v190, v191
	ds_read_b128 v[142:145], v109 offset:144
	v_pk_fma_f32 v[188:189], v[138:139], v[84:85], v[88:89]
	v_pk_fma_f32 v[190:191], v[140:141], v[86:87], v[90:91]
	v_pk_fma_f32 v[192:193], v[130:131], v[100:101], v[104:105]
	v_pk_fma_f32 v[194:195], v[132:133], v[102:103], v[106:107]
	v_cndmask_b32_e64 v146, v138, v146, s[10:11]
	v_cndmask_b32_e64 v147, v139, v147, s[10:11]
	v_cndmask_b32_e64 v148, v140, v148, s[10:11]
	v_cndmask_b32_e64 v149, v141, v149, s[10:11]
	v_cndmask_b32_e64 v134, v130, v134, s[10:11]
	v_cndmask_b32_e64 v135, v131, v135, s[10:11]
	v_cndmask_b32_e64 v136, v132, v136, s[10:11]
	v_cndmask_b32_e64 v137, v133, v137, s[10:11]
	v_fmac_f32_dpp v188, v146, v76 row_ror:2 row_mask:0xf bank_mask:0xf
	v_fmac_f32_dpp v189, v147, v77 row_ror:2 row_mask:0xf bank_mask:0xf
	v_fmac_f32_dpp v190, v148, v78 row_ror:2 row_mask:0xf bank_mask:0xf
	v_fmac_f32_dpp v191, v149, v79 row_ror:2 row_mask:0xf bank_mask:0xf
	v_fmac_f32_dpp v192, v134, v92 row_ror:2 row_mask:0xf bank_mask:0xf
	v_fmac_f32_dpp v193, v135, v93 row_ror:2 row_mask:0xf bank_mask:0xf
	v_fmac_f32_dpp v194, v136, v94 row_ror:2 row_mask:0xf bank_mask:0xf
	v_fmac_f32_dpp v195, v137, v95 row_ror:2 row_mask:0xf bank_mask:0xf
	v_cndmask_b32_e64 v146, v138, v146, s[8:9]
	v_cndmask_b32_e64 v147, v139, v147, s[8:9]
	v_cndmask_b32_e64 v148, v140, v148, s[8:9]
	v_cndmask_b32_e64 v149, v141, v149, s[8:9]
	v_cndmask_b32_e64 v134, v130, v134, s[8:9]
	v_cndmask_b32_e64 v135, v131, v135, s[8:9]
	v_cndmask_b32_e64 v136, v132, v136, s[8:9]
	v_cndmask_b32_e64 v137, v133, v137, s[8:9]
	v_fmac_f32_dpp v188, v146, v80 row_ror:1 row_mask:0xf bank_mask:0xf
	v_fmac_f32_dpp v189, v147, v81 row_ror:1 row_mask:0xf bank_mask:0xf
	v_fmac_f32_dpp v190, v148, v82 row_ror:1 row_mask:0xf bank_mask:0xf
	v_fmac_f32_dpp v191, v149, v83 row_ror:1 row_mask:0xf bank_mask:0xf
	v_fmac_f32_dpp v192, v134, v96 row_ror:1 row_mask:0xf bank_mask:0xf
	v_fmac_f32_dpp v193, v135, v97 row_ror:1 row_mask:0xf bank_mask:0xf
	v_fmac_f32_dpp v194, v136, v98 row_ror:1 row_mask:0xf bank_mask:0xf
	v_fmac_f32_dpp v195, v137, v99 row_ror:1 row_mask:0xf bank_mask:0xf
	v_pk_mul_f32 v[196:197], v[188:189], v[216:217] op_sel_hi:[1,0]
	v_pk_mul_f32 v[198:199], v[190:191], v[216:217] op_sel_hi:[1,0]
	v_exp_f32_e32 v196, v196
	v_exp_f32_e32 v197, v197
	v_exp_f32_e32 v198, v198
	v_exp_f32_e32 v199, v199
	v_pk_add_f32 v[196:197], v[196:197], v[214:215] op_sel_hi:[1,0]
	v_pk_add_f32 v[198:199], v[198:199], v[214:215] op_sel_hi:[1,0]
	v_rcp_f32_e32 v196, v196
	v_rcp_f32_e32 v197, v197
	v_rcp_f32_e32 v198, v198
	v_rcp_f32_e32 v199, v199
	v_pk_mul_f32 v[188:189], v[188:189], v[196:197]
	v_pk_mul_f32 v[190:191], v[190:191], v[198:199]
	v_pk_mul_f32 v[188:189], v[188:189], v[192:193]
	v_pk_mul_f32 v[190:191], v[190:191], v[194:195]
	v_cvt_pk_bf16_f32 v146, v188, v189
	v_cvt_pk_bf16_f32 v147, v190, v191
	ds_read_b128 v[134:137], v109 offset:272
	v_pk_fma_f32 v[188:189], v[126:127], v[84:85], v[88:89]
	v_pk_fma_f32 v[190:191], v[128:129], v[86:87], v[90:91]
	v_pk_fma_f32 v[192:193], v[118:119], v[100:101], v[104:105]
	v_pk_fma_f32 v[194:195], v[120:121], v[102:103], v[106:107]
	v_cndmask_b32_e64 v138, v126, v138, s[10:11]
	v_cndmask_b32_e64 v139, v127, v139, s[10:11]
	v_cndmask_b32_e64 v140, v128, v140, s[10:11]
	v_cndmask_b32_e64 v141, v129, v141, s[10:11]
	v_cndmask_b32_e64 v130, v118, v130, s[10:11]
	v_cndmask_b32_e64 v131, v119, v131, s[10:11]
	v_cndmask_b32_e64 v132, v120, v132, s[10:11]
	v_cndmask_b32_e64 v133, v121, v133, s[10:11]
	v_fmac_f32_dpp v188, v138, v76 row_ror:2 row_mask:0xf bank_mask:0xf
	v_fmac_f32_dpp v189, v139, v77 row_ror:2 row_mask:0xf bank_mask:0xf
	v_fmac_f32_dpp v190, v140, v78 row_ror:2 row_mask:0xf bank_mask:0xf
	v_fmac_f32_dpp v191, v141, v79 row_ror:2 row_mask:0xf bank_mask:0xf
	v_fmac_f32_dpp v192, v130, v92 row_ror:2 row_mask:0xf bank_mask:0xf
	v_fmac_f32_dpp v193, v131, v93 row_ror:2 row_mask:0xf bank_mask:0xf
	v_fmac_f32_dpp v194, v132, v94 row_ror:2 row_mask:0xf bank_mask:0xf
	v_fmac_f32_dpp v195, v133, v95 row_ror:2 row_mask:0xf bank_mask:0xf
	v_cndmask_b32_e64 v138, v126, v138, s[8:9]
	v_cndmask_b32_e64 v139, v127, v139, s[8:9]
	v_cndmask_b32_e64 v140, v128, v140, s[8:9]
	v_cndmask_b32_e64 v141, v129, v141, s[8:9]
	v_cndmask_b32_e64 v130, v118, v130, s[8:9]
	v_cndmask_b32_e64 v131, v119, v131, s[8:9]
	v_cndmask_b32_e64 v132, v120, v132, s[8:9]
	v_cndmask_b32_e64 v133, v121, v133, s[8:9]
	v_fmac_f32_dpp v188, v138, v80 row_ror:1 row_mask:0xf bank_mask:0xf
	v_fmac_f32_dpp v189, v139, v81 row_ror:1 row_mask:0xf bank_mask:0xf
	v_fmac_f32_dpp v190, v140, v82 row_ror:1 row_mask:0xf bank_mask:0xf
	v_fmac_f32_dpp v191, v141, v83 row_ror:1 row_mask:0xf bank_mask:0xf
	v_fmac_f32_dpp v192, v130, v96 row_ror:1 row_mask:0xf bank_mask:0xf
	v_fmac_f32_dpp v193, v131, v97 row_ror:1 row_mask:0xf bank_mask:0xf
	v_fmac_f32_dpp v194, v132, v98 row_ror:1 row_mask:0xf bank_mask:0xf
	v_fmac_f32_dpp v195, v133, v99 row_ror:1 row_mask:0xf bank_mask:0xf
	v_pk_mul_f32 v[196:197], v[188:189], v[216:217] op_sel_hi:[1,0]
	v_pk_mul_f32 v[198:199], v[190:191], v[216:217] op_sel_hi:[1,0]
	v_exp_f32_e32 v196, v196
	v_exp_f32_e32 v197, v197
	v_exp_f32_e32 v198, v198
	v_exp_f32_e32 v199, v199
	v_pk_add_f32 v[196:197], v[196:197], v[214:215] op_sel_hi:[1,0]
	v_pk_add_f32 v[198:199], v[198:199], v[214:215] op_sel_hi:[1,0]
	v_rcp_f32_e32 v196, v196
	v_rcp_f32_e32 v197, v197
	v_rcp_f32_e32 v198, v198
	v_rcp_f32_e32 v199, v199
	v_pk_mul_f32 v[188:189], v[188:189], v[196:197]
	v_pk_mul_f32 v[190:191], v[190:191], v[198:199]
	v_pk_mul_f32 v[188:189], v[188:189], v[192:193]
	v_pk_mul_f32 v[190:191], v[190:191], v[194:195]
	v_cvt_pk_bf16_f32 v138, v188, v189
	v_cvt_pk_bf16_f32 v139, v190, v191
	ds_read_b128 v[130:133], v109 offset:400
	v_pk_fma_f32 v[188:189], v[122:123], v[84:85], v[88:89]
	v_pk_fma_f32 v[190:191], v[124:125], v[86:87], v[90:91]
	v_pk_fma_f32 v[192:193], v[110:111], v[100:101], v[104:105]
	v_pk_fma_f32 v[194:195], v[112:113], v[102:103], v[106:107]
	v_cndmask_b32_e64 v126, v122, v126, s[10:11]
	v_cndmask_b32_e64 v127, v123, v127, s[10:11]
	v_cndmask_b32_e64 v128, v124, v128, s[10:11]
	v_cndmask_b32_e64 v129, v125, v129, s[10:11]
	v_cndmask_b32_e64 v118, v110, v118, s[10:11]
	v_cndmask_b32_e64 v119, v111, v119, s[10:11]
	v_cndmask_b32_e64 v120, v112, v120, s[10:11]
	v_cndmask_b32_e64 v121, v113, v121, s[10:11]
	v_fmac_f32_dpp v188, v126, v76 row_ror:2 row_mask:0xf bank_mask:0xf
	v_fmac_f32_dpp v189, v127, v77 row_ror:2 row_mask:0xf bank_mask:0xf
	v_fmac_f32_dpp v190, v128, v78 row_ror:2 row_mask:0xf bank_mask:0xf
	v_fmac_f32_dpp v191, v129, v79 row_ror:2 row_mask:0xf bank_mask:0xf
	v_fmac_f32_dpp v192, v118, v92 row_ror:2 row_mask:0xf bank_mask:0xf
	v_fmac_f32_dpp v193, v119, v93 row_ror:2 row_mask:0xf bank_mask:0xf
	v_fmac_f32_dpp v194, v120, v94 row_ror:2 row_mask:0xf bank_mask:0xf
	v_fmac_f32_dpp v195, v121, v95 row_ror:2 row_mask:0xf bank_mask:0xf
	v_cndmask_b32_e64 v126, v122, v126, s[8:9]
	v_cndmask_b32_e64 v127, v123, v127, s[8:9]
	v_cndmask_b32_e64 v128, v124, v128, s[8:9]
	v_cndmask_b32_e64 v129, v125, v129, s[8:9]
	v_cndmask_b32_e64 v118, v110, v118, s[8:9]
	v_cndmask_b32_e64 v119, v111, v119, s[8:9]
	v_cndmask_b32_e64 v120, v112, v120, s[8:9]
	v_cndmask_b32_e64 v121, v113, v121, s[8:9]
	v_fmac_f32_dpp v188, v126, v80 row_ror:1 row_mask:0xf bank_mask:0xf
	v_fmac_f32_dpp v189, v127, v81 row_ror:1 row_mask:0xf bank_mask:0xf
	v_fmac_f32_dpp v190, v128, v82 row_ror:1 row_mask:0xf bank_mask:0xf
	v_fmac_f32_dpp v191, v129, v83 row_ror:1 row_mask:0xf bank_mask:0xf
	v_fmac_f32_dpp v192, v118, v96 row_ror:1 row_mask:0xf bank_mask:0xf
	v_fmac_f32_dpp v193, v119, v97 row_ror:1 row_mask:0xf bank_mask:0xf
	v_fmac_f32_dpp v194, v120, v98 row_ror:1 row_mask:0xf bank_mask:0xf
	v_fmac_f32_dpp v195, v121, v99 row_ror:1 row_mask:0xf bank_mask:0xf
	v_pk_mul_f32 v[196:197], v[188:189], v[216:217] op_sel_hi:[1,0]
	v_pk_mul_f32 v[198:199], v[190:191], v[216:217] op_sel_hi:[1,0]
	v_exp_f32_e32 v196, v196
	v_exp_f32_e32 v197, v197
	v_exp_f32_e32 v198, v198
	v_exp_f32_e32 v199, v199
	v_pk_add_f32 v[196:197], v[196:197], v[214:215] op_sel_hi:[1,0]
	v_pk_add_f32 v[198:199], v[198:199], v[214:215] op_sel_hi:[1,0]
	v_rcp_f32_e32 v196, v196
	v_rcp_f32_e32 v197, v197
	v_rcp_f32_e32 v198, v198
	v_rcp_f32_e32 v199, v199
	v_pk_mul_f32 v[188:189], v[188:189], v[196:197]
	v_pk_mul_f32 v[190:191], v[190:191], v[198:199]
	v_pk_mul_f32 v[188:189], v[188:189], v[192:193]
	v_pk_mul_f32 v[190:191], v[190:191], v[194:195]
	v_cvt_pk_bf16_f32 v126, v188, v189
	v_cvt_pk_bf16_f32 v127, v190, v191
	ds_read_b128 v[118:121], v109 offset:528
	v_pk_fma_f32 v[188:189], v[114:115], v[84:85], v[88:89]
	v_pk_fma_f32 v[190:191], v[116:117], v[86:87], v[90:91]
	v_pk_fma_f32 v[192:193], v[68:69], v[100:101], v[104:105]
	v_pk_fma_f32 v[194:195], v[70:71], v[102:103], v[106:107]
	v_cndmask_b32_e64 v122, v114, v122, s[10:11]
	v_cndmask_b32_e64 v123, v115, v123, s[10:11]
	v_cndmask_b32_e64 v124, v116, v124, s[10:11]
	v_cndmask_b32_e64 v125, v117, v125, s[10:11]
	v_cndmask_b32_e64 v110, v68, v110, s[10:11]
	v_cndmask_b32_e64 v111, v69, v111, s[10:11]
	v_cndmask_b32_e64 v112, v70, v112, s[10:11]
	v_cndmask_b32_e64 v113, v71, v113, s[10:11]
	v_fmac_f32_dpp v188, v122, v76 row_ror:2 row_mask:0xf bank_mask:0xf
	v_fmac_f32_dpp v189, v123, v77 row_ror:2 row_mask:0xf bank_mask:0xf
	v_fmac_f32_dpp v190, v124, v78 row_ror:2 row_mask:0xf bank_mask:0xf
	v_fmac_f32_dpp v191, v125, v79 row_ror:2 row_mask:0xf bank_mask:0xf
	v_fmac_f32_dpp v192, v110, v92 row_ror:2 row_mask:0xf bank_mask:0xf
	v_fmac_f32_dpp v193, v111, v93 row_ror:2 row_mask:0xf bank_mask:0xf
	v_fmac_f32_dpp v194, v112, v94 row_ror:2 row_mask:0xf bank_mask:0xf
	v_fmac_f32_dpp v195, v113, v95 row_ror:2 row_mask:0xf bank_mask:0xf
	v_cndmask_b32_e64 v122, v114, v122, s[8:9]
	v_cndmask_b32_e64 v123, v115, v123, s[8:9]
	v_cndmask_b32_e64 v124, v116, v124, s[8:9]
	v_cndmask_b32_e64 v125, v117, v125, s[8:9]
	v_cndmask_b32_e64 v110, v68, v110, s[8:9]
	v_cndmask_b32_e64 v111, v69, v111, s[8:9]
	v_cndmask_b32_e64 v112, v70, v112, s[8:9]
	v_cndmask_b32_e64 v113, v71, v113, s[8:9]
	v_fmac_f32_dpp v188, v122, v80 row_ror:1 row_mask:0xf bank_mask:0xf
	v_fmac_f32_dpp v189, v123, v81 row_ror:1 row_mask:0xf bank_mask:0xf
	v_fmac_f32_dpp v190, v124, v82 row_ror:1 row_mask:0xf bank_mask:0xf
	v_fmac_f32_dpp v191, v125, v83 row_ror:1 row_mask:0xf bank_mask:0xf
	v_fmac_f32_dpp v192, v110, v96 row_ror:1 row_mask:0xf bank_mask:0xf
	v_fmac_f32_dpp v193, v111, v97 row_ror:1 row_mask:0xf bank_mask:0xf
	v_fmac_f32_dpp v194, v112, v98 row_ror:1 row_mask:0xf bank_mask:0xf
	v_fmac_f32_dpp v195, v113, v99 row_ror:1 row_mask:0xf bank_mask:0xf
	v_pk_mul_f32 v[196:197], v[188:189], v[216:217] op_sel_hi:[1,0]
	v_pk_mul_f32 v[198:199], v[190:191], v[216:217] op_sel_hi:[1,0]
	v_exp_f32_e32 v196, v196
	v_exp_f32_e32 v197, v197
	v_exp_f32_e32 v198, v198
	v_exp_f32_e32 v199, v199
	v_pk_add_f32 v[196:197], v[196:197], v[214:215] op_sel_hi:[1,0]
	v_pk_add_f32 v[198:199], v[198:199], v[214:215] op_sel_hi:[1,0]
	v_rcp_f32_e32 v196, v196
	v_rcp_f32_e32 v197, v197
	v_rcp_f32_e32 v198, v198
	v_rcp_f32_e32 v199, v199
	v_pk_mul_f32 v[188:189], v[188:189], v[196:197]
	v_pk_mul_f32 v[190:191], v[190:191], v[198:199]
	v_pk_mul_f32 v[188:189], v[188:189], v[192:193]
	v_pk_mul_f32 v[190:191], v[190:191], v[194:195]
	v_cvt_pk_bf16_f32 v122, v188, v189
	v_cvt_pk_bf16_f32 v123, v190, v191
	ds_read_b128 v[110:113], v109 offset:656
	v_pk_fma_f32 v[188:189], v[72:73], v[84:85], v[88:89]
	v_pk_fma_f32 v[190:191], v[74:75], v[86:87], v[90:91]
	v_pk_fma_f32 v[192:193], v[64:65], v[100:101], v[104:105]
	v_pk_fma_f32 v[194:195], v[66:67], v[102:103], v[106:107]
	v_cndmask_b32_e64 v114, v72, v114, s[10:11]
	v_cndmask_b32_e64 v115, v73, v115, s[10:11]
	v_cndmask_b32_e64 v116, v74, v116, s[10:11]
	v_cndmask_b32_e64 v117, v75, v117, s[10:11]
	v_cndmask_b32_e64 v68, v64, v68, s[10:11]
	v_cndmask_b32_e64 v69, v65, v69, s[10:11]
	v_cndmask_b32_e64 v70, v66, v70, s[10:11]
	v_cndmask_b32_e64 v71, v67, v71, s[10:11]
	v_fmac_f32_dpp v188, v114, v76 row_ror:2 row_mask:0xf bank_mask:0xf
	v_fmac_f32_dpp v189, v115, v77 row_ror:2 row_mask:0xf bank_mask:0xf
	v_fmac_f32_dpp v190, v116, v78 row_ror:2 row_mask:0xf bank_mask:0xf
	v_fmac_f32_dpp v191, v117, v79 row_ror:2 row_mask:0xf bank_mask:0xf
	v_fmac_f32_dpp v192, v68, v92 row_ror:2 row_mask:0xf bank_mask:0xf
	v_fmac_f32_dpp v193, v69, v93 row_ror:2 row_mask:0xf bank_mask:0xf
	v_fmac_f32_dpp v194, v70, v94 row_ror:2 row_mask:0xf bank_mask:0xf
	v_fmac_f32_dpp v195, v71, v95 row_ror:2 row_mask:0xf bank_mask:0xf
	v_cndmask_b32_e64 v114, v72, v114, s[8:9]
	v_cndmask_b32_e64 v115, v73, v115, s[8:9]
	v_cndmask_b32_e64 v116, v74, v116, s[8:9]
	v_cndmask_b32_e64 v117, v75, v117, s[8:9]
	v_cndmask_b32_e64 v68, v64, v68, s[8:9]
	v_cndmask_b32_e64 v69, v65, v69, s[8:9]
	v_cndmask_b32_e64 v70, v66, v70, s[8:9]
	v_cndmask_b32_e64 v71, v67, v71, s[8:9]
	v_fmac_f32_dpp v188, v114, v80 row_ror:1 row_mask:0xf bank_mask:0xf
	v_fmac_f32_dpp v189, v115, v81 row_ror:1 row_mask:0xf bank_mask:0xf
	v_fmac_f32_dpp v190, v116, v82 row_ror:1 row_mask:0xf bank_mask:0xf
	v_fmac_f32_dpp v191, v117, v83 row_ror:1 row_mask:0xf bank_mask:0xf
	v_fmac_f32_dpp v192, v68, v96 row_ror:1 row_mask:0xf bank_mask:0xf
	v_fmac_f32_dpp v193, v69, v97 row_ror:1 row_mask:0xf bank_mask:0xf
	v_fmac_f32_dpp v194, v70, v98 row_ror:1 row_mask:0xf bank_mask:0xf
	v_fmac_f32_dpp v195, v71, v99 row_ror:1 row_mask:0xf bank_mask:0xf
	v_pk_mul_f32 v[196:197], v[188:189], v[216:217] op_sel_hi:[1,0]
	v_pk_mul_f32 v[198:199], v[190:191], v[216:217] op_sel_hi:[1,0]
	v_exp_f32_e32 v196, v196
	v_exp_f32_e32 v197, v197
	v_exp_f32_e32 v198, v198
	v_exp_f32_e32 v199, v199
	v_pk_add_f32 v[196:197], v[196:197], v[214:215] op_sel_hi:[1,0]
	v_pk_add_f32 v[198:199], v[198:199], v[214:215] op_sel_hi:[1,0]
	v_rcp_f32_e32 v196, v196
	v_rcp_f32_e32 v197, v197
	v_rcp_f32_e32 v198, v198
	v_rcp_f32_e32 v199, v199
	v_pk_mul_f32 v[188:189], v[188:189], v[196:197]
	v_pk_mul_f32 v[190:191], v[190:191], v[198:199]
	v_pk_mul_f32 v[188:189], v[188:189], v[192:193]
	v_pk_mul_f32 v[190:191], v[190:191], v[194:195]
	v_cvt_pk_bf16_f32 v114, v188, v189
	v_cvt_pk_bf16_f32 v115, v190, v191
	s_waitcnt lgkmcnt(0)
	s_cmp_lg_u64 s[4:5], 0
	s_cselect_b32 s98, s0, s30
	s_cselect_b32 s99, s1, s28
	v_lshrrev_b32_e32 v196, 6, v222
	s_lshl_b32 s98, s98, 8
	s_add_i32 s98, s98, s56
	s_lshl_b32 s99, s99, 7
	s_add_i32 s99, s99, s49
	s_lshl_b32 s99, s99, 2
	v_and_b32_e32 v197, 63, v222
	v_add_u32_e32 v198, s98, v197
	v_lshlrev_b32_e32 v198, 2, v198
	v_lshrrev_b32_e32 v199, 3, v197
	v_and_b32_e32 v197, 7, v197
	v_readfirstlane_b32 s98, v196
	v_lshrrev_b32_e32 v196, 2, v199
	v_and_b32_e32 v199, 3, v199
	v_cmp_eq_u32_e64 s[100:101], 3, v199
	v_mul_u32_u24_e32 v199, 0xb000, v199
	v_add_u32_e32 v199, 0x0, v199
	v_mov_b32_e32 v188, 0x0
	v_cndmask_b32_e64 v199, v199, v188, s[100:101]
	v_mul_u32_u24_e32 v196, 0x5800, v196
	v_add3_u32 v199, v199, v196, s99
	v_lshl_add_u32 v199, v197, 4, v199
	s_lshl_b32 s100, s98, 9
	s_add_i32 m0, s100, 0x20040
	s_nop 0
	global_load_lds_dword v198, s[12:13]
	v_add_u32_e32 v198, 0x100, v198
	s_add_i32 m0, s100, 0x20140
	s_nop 0
	global_load_lds_dword v198, s[12:13]
	s_lshl_b32 s100, s98, 10
	s_add_i32 m0, s100, 0x21040
	s_mov_b32 exec_lo, 0x00ffffff
	s_mov_b32 exec_hi, 0x00ffffff
	global_load_lds_dwordx4 v199, s[82:83]
	s_mov_b32 exec_lo, 0xff000000
	s_mov_b32 exec_hi, 0xff000000
	global_load_lds_dwordx4 v199, s[84:85]
	s_mov_b64 exec, -1
	s_nop 4
	v_pk_fma_f32 v[188:189], v[60:61], v[134:135], v[130:131]
	v_pk_fma_f32 v[190:191], v[62:63], v[136:137], v[132:133]
	v_pk_fma_f32 v[192:193], v[56:57], v[204:205], v[208:209]
	v_pk_fma_f32 v[194:195], v[58:59], v[206:207], v[210:211]
	v_fmac_f32_dpp v188, v60, v142 row_shr:1 row_mask:0xf bank_mask:0xf
	v_fmac_f32_dpp v189, v61, v143 row_shr:1 row_mask:0xf bank_mask:0xf
	v_fmac_f32_dpp v190, v62, v144 row_shr:1 row_mask:0xf bank_mask:0xf
	v_fmac_f32_dpp v191, v63, v145 row_shr:1 row_mask:0xf bank_mask:0xf
	v_fmac_f32_dpp v192, v56, v110 row_shr:1 row_mask:0xf bank_mask:0xf
	v_fmac_f32_dpp v193, v57, v111 row_shr:1 row_mask:0xf bank_mask:0xf
	v_fmac_f32_dpp v194, v58, v112 row_shr:1 row_mask:0xf bank_mask:0xf
	v_fmac_f32_dpp v195, v59, v113 row_shr:1 row_mask:0xf bank_mask:0xf
	v_fmac_f32_dpp v188, v60, v154 row_shr:2 row_mask:0xf bank_mask:0xf
	v_fmac_f32_dpp v189, v61, v155 row_shr:2 row_mask:0xf bank_mask:0xf
	v_fmac_f32_dpp v190, v62, v156 row_shr:2 row_mask:0xf bank_mask:0xf
	v_fmac_f32_dpp v191, v63, v157 row_shr:2 row_mask:0xf bank_mask:0xf
	v_fmac_f32_dpp v192, v56, v118 row_shr:2 row_mask:0xf bank_mask:0xf
	v_fmac_f32_dpp v193, v57, v119 row_shr:2 row_mask:0xf bank_mask:0xf
	v_fmac_f32_dpp v194, v58, v120 row_shr:2 row_mask:0xf bank_mask:0xf
	v_fmac_f32_dpp v195, v59, v121 row_shr:2 row_mask:0xf bank_mask:0xf
	v_pk_mul_f32 v[196:197], v[188:189], v[216:217] op_sel_hi:[1,0]
	v_pk_mul_f32 v[198:199], v[190:191], v[216:217] op_sel_hi:[1,0]
	v_exp_f32_e32 v196, v196
	v_exp_f32_e32 v197, v197
	v_exp_f32_e32 v198, v198
	v_exp_f32_e32 v199, v199
	v_pk_add_f32 v[196:197], v[196:197], v[214:215] op_sel_hi:[1,0]
	v_pk_add_f32 v[198:199], v[198:199], v[214:215] op_sel_hi:[1,0]
	v_rcp_f32_e32 v196, v196
	v_rcp_f32_e32 v197, v197
	v_rcp_f32_e32 v198, v198
	v_rcp_f32_e32 v199, v199
	v_pk_mul_f32 v[188:189], v[188:189], v[196:197]
	v_pk_mul_f32 v[190:191], v[190:191], v[198:199]
	v_pk_mul_f32 v[188:189], v[188:189], v[192:193]
	v_pk_mul_f32 v[190:191], v[190:191], v[194:195]
	v_cvt_pk_bf16_f32 v202, v188, v189
	v_cvt_pk_bf16_f32 v203, v190, v191
	s_mov_b64 exec, vcc
	global_store_dwordx4 v215, v[200:203], s[96:97] nt
	s_mov_b64 exec, -1
	v_pk_fma_f32 v[188:189], v[52:53], v[134:135], v[130:131]
	v_pk_fma_f32 v[190:191], v[54:55], v[136:137], v[132:133]
	v_pk_fma_f32 v[192:193], v[44:45], v[204:205], v[208:209]
	v_pk_fma_f32 v[194:195], v[46:47], v[206:207], v[210:211]
	v_cndmask_b32_e64 v60, v52, v60, s[10:11]
	v_cndmask_b32_e64 v61, v53, v61, s[10:11]
	v_cndmask_b32_e64 v62, v54, v62, s[10:11]
	v_cndmask_b32_e64 v63, v55, v63, s[10:11]
	v_cndmask_b32_e64 v56, v44, v56, s[10:11]
	v_cndmask_b32_e64 v57, v45, v57, s[10:11]
	v_cndmask_b32_e64 v58, v46, v58, s[10:11]
	v_cndmask_b32_e64 v59, v47, v59, s[10:11]
	v_fmac_f32_dpp v188, v60, v154 row_ror:2 row_mask:0xf bank_mask:0xf
	v_fmac_f32_dpp v189, v61, v155 row_ror:2 row_mask:0xf bank_mask:0xf
	v_fmac_f32_dpp v190, v62, v156 row_ror:2 row_mask:0xf bank_mask:0xf
	v_fmac_f32_dpp v191, v63, v157 row_ror:2 row_mask:0xf bank_mask:0xf
	v_fmac_f32_dpp v192, v56, v118 row_ror:2 row_mask:0xf bank_mask:0xf
	v_fmac_f32_dpp v193, v57, v119 row_ror:2 row_mask:0xf bank_mask:0xf
	v_fmac_f32_dpp v194, v58, v120 row_ror:2 row_mask:0xf bank_mask:0xf
	v_fmac_f32_dpp v195, v59, v121 row_ror:2 row_mask:0xf bank_mask:0xf
	v_cndmask_b32_e64 v60, v52, v60, s[8:9]
	v_cndmask_b32_e64 v61, v53, v61, s[8:9]
	v_cndmask_b32_e64 v62, v54, v62, s[8:9]
	v_cndmask_b32_e64 v63, v55, v63, s[8:9]
	v_cndmask_b32_e64 v56, v44, v56, s[8:9]
	v_cndmask_b32_e64 v57, v45, v57, s[8:9]
	v_cndmask_b32_e64 v58, v46, v58, s[8:9]
	v_cndmask_b32_e64 v59, v47, v59, s[8:9]
	v_fmac_f32_dpp v188, v60, v142 row_ror:1 row_mask:0xf bank_mask:0xf
	v_fmac_f32_dpp v189, v61, v143 row_ror:1 row_mask:0xf bank_mask:0xf
	v_fmac_f32_dpp v190, v62, v144 row_ror:1 row_mask:0xf bank_mask:0xf
	v_fmac_f32_dpp v191, v63, v145 row_ror:1 row_mask:0xf bank_mask:0xf
	v_fmac_f32_dpp v192, v56, v110 row_ror:1 row_mask:0xf bank_mask:0xf
	v_fmac_f32_dpp v193, v57, v111 row_ror:1 row_mask:0xf bank_mask:0xf
	v_fmac_f32_dpp v194, v58, v112 row_ror:1 row_mask:0xf bank_mask:0xf
	v_fmac_f32_dpp v195, v59, v113 row_ror:1 row_mask:0xf bank_mask:0xf
	v_pk_mul_f32 v[196:197], v[188:189], v[216:217] op_sel_hi:[1,0]
	v_pk_mul_f32 v[198:199], v[190:191], v[216:217] op_sel_hi:[1,0]
	v_exp_f32_e32 v196, v196
	v_exp_f32_e32 v197, v197
	v_exp_f32_e32 v198, v198
	v_exp_f32_e32 v199, v199
	v_pk_add_f32 v[196:197], v[196:197], v[214:215] op_sel_hi:[1,0]
	v_pk_add_f32 v[198:199], v[198:199], v[214:215] op_sel_hi:[1,0]
	v_rcp_f32_e32 v196, v196
	v_rcp_f32_e32 v197, v197
	v_rcp_f32_e32 v198, v198
	v_rcp_f32_e32 v199, v199
	v_pk_mul_f32 v[188:189], v[188:189], v[196:197]
	v_pk_mul_f32 v[190:191], v[190:191], v[198:199]
	v_pk_mul_f32 v[188:189], v[188:189], v[192:193]
	v_pk_mul_f32 v[190:191], v[190:191], v[194:195]
	v_cvt_pk_bf16_f32 v160, v188, v189
	v_cvt_pk_bf16_f32 v161, v190, v191
	v_add_u32_e32 v213, 0x2c000, v215
	global_store_dwordx4 v213, v[158:161], s[96:97] nt
	v_pk_fma_f32 v[188:189], v[48:49], v[134:135], v[130:131]
	v_pk_fma_f32 v[190:191], v[50:51], v[136:137], v[132:133]
	v_pk_fma_f32 v[192:193], v[36:37], v[204:205], v[208:209]
	v_pk_fma_f32 v[194:195], v[38:39], v[206:207], v[210:211]
	v_cndmask_b32_e64 v52, v48, v52, s[10:11]
	v_cndmask_b32_e64 v53, v49, v53, s[10:11]
	v_cndmask_b32_e64 v54, v50, v54, s[10:11]
	v_cndmask_b32_e64 v55, v51, v55, s[10:11]
	v_cndmask_b32_e64 v44, v36, v44, s[10:11]
	v_cndmask_b32_e64 v45, v37, v45, s[10:11]
	v_cndmask_b32_e64 v46, v38, v46, s[10:11]
	v_cndmask_b32_e64 v47, v39, v47, s[10:11]
	v_fmac_f32_dpp v188, v52, v154 row_ror:2 row_mask:0xf bank_mask:0xf
	v_fmac_f32_dpp v189, v53, v155 row_ror:2 row_mask:0xf bank_mask:0xf
	v_fmac_f32_dpp v190, v54, v156 row_ror:2 row_mask:0xf bank_mask:0xf
	v_fmac_f32_dpp v191, v55, v157 row_ror:2 row_mask:0xf bank_mask:0xf
	v_fmac_f32_dpp v192, v44, v118 row_ror:2 row_mask:0xf bank_mask:0xf
	v_fmac_f32_dpp v193, v45, v119 row_ror:2 row_mask:0xf bank_mask:0xf
	v_fmac_f32_dpp v194, v46, v120 row_ror:2 row_mask:0xf bank_mask:0xf
	v_fmac_f32_dpp v195, v47, v121 row_ror:2 row_mask:0xf bank_mask:0xf
	v_cndmask_b32_e64 v52, v48, v52, s[8:9]
	v_cndmask_b32_e64 v53, v49, v53, s[8:9]
	v_cndmask_b32_e64 v54, v50, v54, s[8:9]
	v_cndmask_b32_e64 v55, v51, v55, s[8:9]
	v_cndmask_b32_e64 v44, v36, v44, s[8:9]
	v_cndmask_b32_e64 v45, v37, v45, s[8:9]
	v_cndmask_b32_e64 v46, v38, v46, s[8:9]
	v_cndmask_b32_e64 v47, v39, v47, s[8:9]
	v_fmac_f32_dpp v188, v52, v142 row_ror:1 row_mask:0xf bank_mask:0xf
	v_fmac_f32_dpp v189, v53, v143 row_ror:1 row_mask:0xf bank_mask:0xf
	v_fmac_f32_dpp v190, v54, v144 row_ror:1 row_mask:0xf bank_mask:0xf
	v_fmac_f32_dpp v191, v55, v145 row_ror:1 row_mask:0xf bank_mask:0xf
	v_fmac_f32_dpp v192, v44, v110 row_ror:1 row_mask:0xf bank_mask:0xf
	v_fmac_f32_dpp v193, v45, v111 row_ror:1 row_mask:0xf bank_mask:0xf
	v_fmac_f32_dpp v194, v46, v112 row_ror:1 row_mask:0xf bank_mask:0xf
	v_fmac_f32_dpp v195, v47, v113 row_ror:1 row_mask:0xf bank_mask:0xf
	v_pk_mul_f32 v[196:197], v[188:189], v[216:217] op_sel_hi:[1,0]
	v_pk_mul_f32 v[198:199], v[190:191], v[216:217] op_sel_hi:[1,0]
	v_exp_f32_e32 v196, v196
	v_exp_f32_e32 v197, v197
	v_exp_f32_e32 v198, v198
	v_exp_f32_e32 v199, v199
	v_pk_add_f32 v[196:197], v[196:197], v[214:215] op_sel_hi:[1,0]
	v_pk_add_f32 v[198:199], v[198:199], v[214:215] op_sel_hi:[1,0]
	v_rcp_f32_e32 v196, v196
	v_rcp_f32_e32 v197, v197
	v_rcp_f32_e32 v198, v198
	v_rcp_f32_e32 v199, v199
	v_pk_mul_f32 v[188:189], v[188:189], v[196:197]
	v_pk_mul_f32 v[190:191], v[190:191], v[198:199]
	v_pk_mul_f32 v[188:189], v[188:189], v[192:193]
	v_pk_mul_f32 v[190:191], v[190:191], v[194:195]
	v_cvt_pk_bf16_f32 v152, v188, v189
	v_cvt_pk_bf16_f32 v153, v190, v191
	v_add_u32_e32 v213, 0x58000, v215
	global_store_dwordx4 v213, v[150:153], s[96:97] nt
	v_pk_fma_f32 v[188:189], v[40:41], v[134:135], v[130:131]
	v_pk_fma_f32 v[190:191], v[42:43], v[136:137], v[132:133]
	v_pk_fma_f32 v[192:193], v[32:33], v[204:205], v[208:209]
	v_pk_fma_f32 v[194:195], v[34:35], v[206:207], v[210:211]
	v_cndmask_b32_e64 v48, v40, v48, s[10:11]
	v_cndmask_b32_e64 v49, v41, v49, s[10:11]
	v_cndmask_b32_e64 v50, v42, v50, s[10:11]
	v_cndmask_b32_e64 v51, v43, v51, s[10:11]
	v_cndmask_b32_e64 v36, v32, v36, s[10:11]
	v_cndmask_b32_e64 v37, v33, v37, s[10:11]
	v_cndmask_b32_e64 v38, v34, v38, s[10:11]
	v_cndmask_b32_e64 v39, v35, v39, s[10:11]
	v_fmac_f32_dpp v188, v48, v154 row_ror:2 row_mask:0xf bank_mask:0xf
	v_fmac_f32_dpp v189, v49, v155 row_ror:2 row_mask:0xf bank_mask:0xf
	v_fmac_f32_dpp v190, v50, v156 row_ror:2 row_mask:0xf bank_mask:0xf
	v_fmac_f32_dpp v191, v51, v157 row_ror:2 row_mask:0xf bank_mask:0xf
	v_fmac_f32_dpp v192, v36, v118 row_ror:2 row_mask:0xf bank_mask:0xf
	v_fmac_f32_dpp v193, v37, v119 row_ror:2 row_mask:0xf bank_mask:0xf
	v_fmac_f32_dpp v194, v38, v120 row_ror:2 row_mask:0xf bank_mask:0xf
	v_fmac_f32_dpp v195, v39, v121 row_ror:2 row_mask:0xf bank_mask:0xf
	v_cndmask_b32_e64 v48, v40, v48, s[8:9]
	v_cndmask_b32_e64 v49, v41, v49, s[8:9]
	v_cndmask_b32_e64 v50, v42, v50, s[8:9]
	v_cndmask_b32_e64 v51, v43, v51, s[8:9]
	v_cndmask_b32_e64 v36, v32, v36, s[8:9]
	v_cndmask_b32_e64 v37, v33, v37, s[8:9]
	v_cndmask_b32_e64 v38, v34, v38, s[8:9]
	v_cndmask_b32_e64 v39, v35, v39, s[8:9]
	v_fmac_f32_dpp v188, v48, v142 row_ror:1 row_mask:0xf bank_mask:0xf
	v_fmac_f32_dpp v189, v49, v143 row_ror:1 row_mask:0xf bank_mask:0xf
	v_fmac_f32_dpp v190, v50, v144 row_ror:1 row_mask:0xf bank_mask:0xf
	v_fmac_f32_dpp v191, v51, v145 row_ror:1 row_mask:0xf bank_mask:0xf
	v_fmac_f32_dpp v192, v36, v110 row_ror:1 row_mask:0xf bank_mask:0xf
	v_fmac_f32_dpp v193, v37, v111 row_ror:1 row_mask:0xf bank_mask:0xf
	v_fmac_f32_dpp v194, v38, v112 row_ror:1 row_mask:0xf bank_mask:0xf
	v_fmac_f32_dpp v195, v39, v113 row_ror:1 row_mask:0xf bank_mask:0xf
	v_pk_mul_f32 v[196:197], v[188:189], v[216:217] op_sel_hi:[1,0]
	v_pk_mul_f32 v[198:199], v[190:191], v[216:217] op_sel_hi:[1,0]
	v_exp_f32_e32 v196, v196
	v_exp_f32_e32 v197, v197
	v_exp_f32_e32 v198, v198
	v_exp_f32_e32 v199, v199
	v_pk_add_f32 v[196:197], v[196:197], v[214:215] op_sel_hi:[1,0]
	v_pk_add_f32 v[198:199], v[198:199], v[214:215] op_sel_hi:[1,0]
	v_rcp_f32_e32 v196, v196
	v_rcp_f32_e32 v197, v197
	v_rcp_f32_e32 v198, v198
	v_rcp_f32_e32 v199, v199
	v_pk_mul_f32 v[188:189], v[188:189], v[196:197]
	v_pk_mul_f32 v[190:191], v[190:191], v[198:199]
	v_pk_mul_f32 v[188:189], v[188:189], v[192:193]
	v_pk_mul_f32 v[190:191], v[190:191], v[194:195]
	v_cvt_pk_bf16_f32 v148, v188, v189
	v_cvt_pk_bf16_f32 v149, v190, v191
	v_add_u32_e32 v213, 0x84000, v215
	global_store_dwordx4 v213, v[146:149], s[96:97] nt
	v_pk_fma_f32 v[188:189], v[28:29], v[134:135], v[130:131]
	v_pk_fma_f32 v[190:191], v[30:31], v[136:137], v[132:133]
	v_pk_fma_f32 v[192:193], v[16:17], v[204:205], v[208:209]
	v_pk_fma_f32 v[194:195], v[18:19], v[206:207], v[210:211]
	v_cndmask_b32_e64 v40, v28, v40, s[10:11]
	v_cndmask_b32_e64 v41, v29, v41, s[10:11]
	v_cndmask_b32_e64 v42, v30, v42, s[10:11]
	v_cndmask_b32_e64 v43, v31, v43, s[10:11]
	v_cndmask_b32_e64 v32, v16, v32, s[10:11]
	v_cndmask_b32_e64 v33, v17, v33, s[10:11]
	v_cndmask_b32_e64 v34, v18, v34, s[10:11]
	v_cndmask_b32_e64 v35, v19, v35, s[10:11]
	v_fmac_f32_dpp v188, v40, v154 row_ror:2 row_mask:0xf bank_mask:0xf
	v_fmac_f32_dpp v189, v41, v155 row_ror:2 row_mask:0xf bank_mask:0xf
	v_fmac_f32_dpp v190, v42, v156 row_ror:2 row_mask:0xf bank_mask:0xf
	v_fmac_f32_dpp v191, v43, v157 row_ror:2 row_mask:0xf bank_mask:0xf
	v_fmac_f32_dpp v192, v32, v118 row_ror:2 row_mask:0xf bank_mask:0xf
	v_fmac_f32_dpp v193, v33, v119 row_ror:2 row_mask:0xf bank_mask:0xf
	v_fmac_f32_dpp v194, v34, v120 row_ror:2 row_mask:0xf bank_mask:0xf
	v_fmac_f32_dpp v195, v35, v121 row_ror:2 row_mask:0xf bank_mask:0xf
	v_cndmask_b32_e64 v40, v28, v40, s[8:9]
	v_cndmask_b32_e64 v41, v29, v41, s[8:9]
	v_cndmask_b32_e64 v42, v30, v42, s[8:9]
	v_cndmask_b32_e64 v43, v31, v43, s[8:9]
	v_cndmask_b32_e64 v32, v16, v32, s[8:9]
	v_cndmask_b32_e64 v33, v17, v33, s[8:9]
	v_cndmask_b32_e64 v34, v18, v34, s[8:9]
	v_cndmask_b32_e64 v35, v19, v35, s[8:9]
	v_fmac_f32_dpp v188, v40, v142 row_ror:1 row_mask:0xf bank_mask:0xf
	v_fmac_f32_dpp v189, v41, v143 row_ror:1 row_mask:0xf bank_mask:0xf
	v_fmac_f32_dpp v190, v42, v144 row_ror:1 row_mask:0xf bank_mask:0xf
	v_fmac_f32_dpp v191, v43, v145 row_ror:1 row_mask:0xf bank_mask:0xf
	v_fmac_f32_dpp v192, v32, v110 row_ror:1 row_mask:0xf bank_mask:0xf
	v_fmac_f32_dpp v193, v33, v111 row_ror:1 row_mask:0xf bank_mask:0xf
	v_fmac_f32_dpp v194, v34, v112 row_ror:1 row_mask:0xf bank_mask:0xf
	v_fmac_f32_dpp v195, v35, v113 row_ror:1 row_mask:0xf bank_mask:0xf
	v_pk_mul_f32 v[196:197], v[188:189], v[216:217] op_sel_hi:[1,0]
	v_pk_mul_f32 v[198:199], v[190:191], v[216:217] op_sel_hi:[1,0]
	v_exp_f32_e32 v196, v196
	v_exp_f32_e32 v197, v197
	v_exp_f32_e32 v198, v198
	v_exp_f32_e32 v199, v199
	v_pk_add_f32 v[196:197], v[196:197], v[214:215] op_sel_hi:[1,0]
	v_pk_add_f32 v[198:199], v[198:199], v[214:215] op_sel_hi:[1,0]
	v_rcp_f32_e32 v196, v196
	v_rcp_f32_e32 v197, v197
	v_rcp_f32_e32 v198, v198
	v_rcp_f32_e32 v199, v199
	v_pk_mul_f32 v[188:189], v[188:189], v[196:197]
	v_pk_mul_f32 v[190:191], v[190:191], v[198:199]
	v_pk_mul_f32 v[188:189], v[188:189], v[192:193]
	v_pk_mul_f32 v[190:191], v[190:191], v[194:195]
	v_cvt_pk_bf16_f32 v140, v188, v189
	v_cvt_pk_bf16_f32 v141, v190, v191
	v_add_u32_e32 v213, 0xb0000, v215
	global_store_dwordx4 v213, v[138:141], s[96:97] nt
	v_pk_fma_f32 v[188:189], v[24:25], v[134:135], v[130:131]
	v_pk_fma_f32 v[190:191], v[26:27], v[136:137], v[132:133]
	v_pk_fma_f32 v[192:193], v[12:13], v[204:205], v[208:209]
	v_pk_fma_f32 v[194:195], v[14:15], v[206:207], v[210:211]
	v_cndmask_b32_e64 v28, v24, v28, s[10:11]
	v_cndmask_b32_e64 v29, v25, v29, s[10:11]
	v_cndmask_b32_e64 v30, v26, v30, s[10:11]
	v_cndmask_b32_e64 v31, v27, v31, s[10:11]
	v_cndmask_b32_e64 v16, v12, v16, s[10:11]
	v_cndmask_b32_e64 v17, v13, v17, s[10:11]
	v_cndmask_b32_e64 v18, v14, v18, s[10:11]
	v_cndmask_b32_e64 v19, v15, v19, s[10:11]
	v_fmac_f32_dpp v188, v28, v154 row_ror:2 row_mask:0xf bank_mask:0xf
	v_fmac_f32_dpp v189, v29, v155 row_ror:2 row_mask:0xf bank_mask:0xf
	v_fmac_f32_dpp v190, v30, v156 row_ror:2 row_mask:0xf bank_mask:0xf
	v_fmac_f32_dpp v191, v31, v157 row_ror:2 row_mask:0xf bank_mask:0xf
	v_fmac_f32_dpp v192, v16, v118 row_ror:2 row_mask:0xf bank_mask:0xf
	v_fmac_f32_dpp v193, v17, v119 row_ror:2 row_mask:0xf bank_mask:0xf
	v_fmac_f32_dpp v194, v18, v120 row_ror:2 row_mask:0xf bank_mask:0xf
	v_fmac_f32_dpp v195, v19, v121 row_ror:2 row_mask:0xf bank_mask:0xf
	v_cndmask_b32_e64 v28, v24, v28, s[8:9]
	v_cndmask_b32_e64 v29, v25, v29, s[8:9]
	v_cndmask_b32_e64 v30, v26, v30, s[8:9]
	v_cndmask_b32_e64 v31, v27, v31, s[8:9]
	v_cndmask_b32_e64 v16, v12, v16, s[8:9]
	v_cndmask_b32_e64 v17, v13, v17, s[8:9]
	v_cndmask_b32_e64 v18, v14, v18, s[8:9]
	v_cndmask_b32_e64 v19, v15, v19, s[8:9]
	v_fmac_f32_dpp v188, v28, v142 row_ror:1 row_mask:0xf bank_mask:0xf
	v_fmac_f32_dpp v189, v29, v143 row_ror:1 row_mask:0xf bank_mask:0xf
	v_fmac_f32_dpp v190, v30, v144 row_ror:1 row_mask:0xf bank_mask:0xf
	v_fmac_f32_dpp v191, v31, v145 row_ror:1 row_mask:0xf bank_mask:0xf
	v_fmac_f32_dpp v192, v16, v110 row_ror:1 row_mask:0xf bank_mask:0xf
	v_fmac_f32_dpp v193, v17, v111 row_ror:1 row_mask:0xf bank_mask:0xf
	v_fmac_f32_dpp v194, v18, v112 row_ror:1 row_mask:0xf bank_mask:0xf
	v_fmac_f32_dpp v195, v19, v113 row_ror:1 row_mask:0xf bank_mask:0xf
	v_pk_mul_f32 v[196:197], v[188:189], v[216:217] op_sel_hi:[1,0]
	v_pk_mul_f32 v[198:199], v[190:191], v[216:217] op_sel_hi:[1,0]
	v_exp_f32_e32 v196, v196
	v_exp_f32_e32 v197, v197
	v_exp_f32_e32 v198, v198
	v_exp_f32_e32 v199, v199
	v_pk_add_f32 v[196:197], v[196:197], v[214:215] op_sel_hi:[1,0]
	v_pk_add_f32 v[198:199], v[198:199], v[214:215] op_sel_hi:[1,0]
	v_rcp_f32_e32 v196, v196
	v_rcp_f32_e32 v197, v197
	v_rcp_f32_e32 v198, v198
	v_rcp_f32_e32 v199, v199
	v_pk_mul_f32 v[188:189], v[188:189], v[196:197]
	v_pk_mul_f32 v[190:191], v[190:191], v[198:199]
	v_pk_mul_f32 v[188:189], v[188:189], v[192:193]
	v_pk_mul_f32 v[190:191], v[190:191], v[194:195]
	v_cvt_pk_bf16_f32 v128, v188, v189
	v_cvt_pk_bf16_f32 v129, v190, v191
	v_add_u32_e32 v213, 0xdc000, v215
	global_store_dwordx4 v213, v[126:129], s[96:97] nt
	v_pk_fma_f32 v[188:189], v[20:21], v[134:135], v[130:131]
	v_pk_fma_f32 v[190:191], v[22:23], v[136:137], v[132:133]
	v_pk_fma_f32 v[192:193], v[8:9], v[204:205], v[208:209]
	v_pk_fma_f32 v[194:195], v[10:11], v[206:207], v[210:211]
	v_cndmask_b32_e64 v24, v20, v24, s[10:11]
	v_cndmask_b32_e64 v25, v21, v25, s[10:11]
	v_cndmask_b32_e64 v26, v22, v26, s[10:11]
	v_cndmask_b32_e64 v27, v23, v27, s[10:11]
	v_cndmask_b32_e64 v12, v8, v12, s[10:11]
	v_cndmask_b32_e64 v13, v9, v13, s[10:11]
	v_cndmask_b32_e64 v14, v10, v14, s[10:11]
	v_cndmask_b32_e64 v15, v11, v15, s[10:11]
	v_fmac_f32_dpp v188, v24, v154 row_ror:2 row_mask:0xf bank_mask:0xf
	v_fmac_f32_dpp v189, v25, v155 row_ror:2 row_mask:0xf bank_mask:0xf
	v_fmac_f32_dpp v190, v26, v156 row_ror:2 row_mask:0xf bank_mask:0xf
	v_fmac_f32_dpp v191, v27, v157 row_ror:2 row_mask:0xf bank_mask:0xf
	v_fmac_f32_dpp v192, v12, v118 row_ror:2 row_mask:0xf bank_mask:0xf
	v_fmac_f32_dpp v193, v13, v119 row_ror:2 row_mask:0xf bank_mask:0xf
	v_fmac_f32_dpp v194, v14, v120 row_ror:2 row_mask:0xf bank_mask:0xf
	v_fmac_f32_dpp v195, v15, v121 row_ror:2 row_mask:0xf bank_mask:0xf
	v_cndmask_b32_e64 v24, v20, v24, s[8:9]
	v_cndmask_b32_e64 v25, v21, v25, s[8:9]
	v_cndmask_b32_e64 v26, v22, v26, s[8:9]
	v_cndmask_b32_e64 v27, v23, v27, s[8:9]
	v_cndmask_b32_e64 v12, v8, v12, s[8:9]
	v_cndmask_b32_e64 v13, v9, v13, s[8:9]
	v_cndmask_b32_e64 v14, v10, v14, s[8:9]
	v_cndmask_b32_e64 v15, v11, v15, s[8:9]
	v_fmac_f32_dpp v188, v24, v142 row_ror:1 row_mask:0xf bank_mask:0xf
	v_fmac_f32_dpp v189, v25, v143 row_ror:1 row_mask:0xf bank_mask:0xf
	v_fmac_f32_dpp v190, v26, v144 row_ror:1 row_mask:0xf bank_mask:0xf
	v_fmac_f32_dpp v191, v27, v145 row_ror:1 row_mask:0xf bank_mask:0xf
	v_fmac_f32_dpp v192, v12, v110 row_ror:1 row_mask:0xf bank_mask:0xf
	v_fmac_f32_dpp v193, v13, v111 row_ror:1 row_mask:0xf bank_mask:0xf
	v_fmac_f32_dpp v194, v14, v112 row_ror:1 row_mask:0xf bank_mask:0xf
	v_fmac_f32_dpp v195, v15, v113 row_ror:1 row_mask:0xf bank_mask:0xf
	v_pk_mul_f32 v[196:197], v[188:189], v[216:217] op_sel_hi:[1,0]
	v_pk_mul_f32 v[198:199], v[190:191], v[216:217] op_sel_hi:[1,0]
	v_exp_f32_e32 v196, v196
	v_exp_f32_e32 v197, v197
	v_exp_f32_e32 v198, v198
	v_exp_f32_e32 v199, v199
	v_pk_add_f32 v[196:197], v[196:197], v[214:215] op_sel_hi:[1,0]
	v_pk_add_f32 v[198:199], v[198:199], v[214:215] op_sel_hi:[1,0]
	v_rcp_f32_e32 v196, v196
	v_rcp_f32_e32 v197, v197
	v_rcp_f32_e32 v198, v198
	v_rcp_f32_e32 v199, v199
	v_pk_mul_f32 v[188:189], v[188:189], v[196:197]
	v_pk_mul_f32 v[190:191], v[190:191], v[198:199]
	v_pk_mul_f32 v[188:189], v[188:189], v[192:193]
	v_pk_mul_f32 v[190:191], v[190:191], v[194:195]
	v_cvt_pk_bf16_f32 v124, v188, v189
	v_cvt_pk_bf16_f32 v125, v190, v191
	v_add_u32_e32 v213, 0x108000, v215
	global_store_dwordx4 v213, v[122:125], s[96:97] nt
	v_pk_fma_f32 v[188:189], v[4:5], v[134:135], v[130:131]
	v_pk_fma_f32 v[190:191], v[6:7], v[136:137], v[132:133]
	v_pk_fma_f32 v[192:193], v[0:1], v[204:205], v[208:209]
	v_pk_fma_f32 v[194:195], v[2:3], v[206:207], v[210:211]
	v_cndmask_b32_e64 v20, v4, v20, s[10:11]
	v_cndmask_b32_e64 v21, v5, v21, s[10:11]
	v_cndmask_b32_e64 v22, v6, v22, s[10:11]
	v_cndmask_b32_e64 v23, v7, v23, s[10:11]
	v_cndmask_b32_e64 v8, v0, v8, s[10:11]
	v_cndmask_b32_e64 v9, v1, v9, s[10:11]
	v_cndmask_b32_e64 v10, v2, v10, s[10:11]
	v_cndmask_b32_e64 v11, v3, v11, s[10:11]
	v_fmac_f32_dpp v188, v20, v154 row_ror:2 row_mask:0xf bank_mask:0xf
	v_fmac_f32_dpp v189, v21, v155 row_ror:2 row_mask:0xf bank_mask:0xf
	v_fmac_f32_dpp v190, v22, v156 row_ror:2 row_mask:0xf bank_mask:0xf
	v_fmac_f32_dpp v191, v23, v157 row_ror:2 row_mask:0xf bank_mask:0xf
	v_fmac_f32_dpp v192, v8, v118 row_ror:2 row_mask:0xf bank_mask:0xf
	v_fmac_f32_dpp v193, v9, v119 row_ror:2 row_mask:0xf bank_mask:0xf
	v_fmac_f32_dpp v194, v10, v120 row_ror:2 row_mask:0xf bank_mask:0xf
	v_fmac_f32_dpp v195, v11, v121 row_ror:2 row_mask:0xf bank_mask:0xf
	v_cndmask_b32_e64 v20, v4, v20, s[8:9]
	v_cndmask_b32_e64 v21, v5, v21, s[8:9]
	v_cndmask_b32_e64 v22, v6, v22, s[8:9]
	v_cndmask_b32_e64 v23, v7, v23, s[8:9]
	v_cndmask_b32_e64 v8, v0, v8, s[8:9]
	v_cndmask_b32_e64 v9, v1, v9, s[8:9]
	v_cndmask_b32_e64 v10, v2, v10, s[8:9]
	v_cndmask_b32_e64 v11, v3, v11, s[8:9]
	v_fmac_f32_dpp v188, v20, v142 row_ror:1 row_mask:0xf bank_mask:0xf
	v_fmac_f32_dpp v189, v21, v143 row_ror:1 row_mask:0xf bank_mask:0xf
	v_fmac_f32_dpp v190, v22, v144 row_ror:1 row_mask:0xf bank_mask:0xf
	v_fmac_f32_dpp v191, v23, v145 row_ror:1 row_mask:0xf bank_mask:0xf
	v_fmac_f32_dpp v192, v8, v110 row_ror:1 row_mask:0xf bank_mask:0xf
	v_fmac_f32_dpp v193, v9, v111 row_ror:1 row_mask:0xf bank_mask:0xf
	v_fmac_f32_dpp v194, v10, v112 row_ror:1 row_mask:0xf bank_mask:0xf
	v_fmac_f32_dpp v195, v11, v113 row_ror:1 row_mask:0xf bank_mask:0xf
	v_pk_mul_f32 v[196:197], v[188:189], v[216:217] op_sel_hi:[1,0]
	v_pk_mul_f32 v[198:199], v[190:191], v[216:217] op_sel_hi:[1,0]
	v_exp_f32_e32 v196, v196
	v_exp_f32_e32 v197, v197
	v_exp_f32_e32 v198, v198
	v_exp_f32_e32 v199, v199
	v_pk_add_f32 v[196:197], v[196:197], v[214:215] op_sel_hi:[1,0]
	v_pk_add_f32 v[198:199], v[198:199], v[214:215] op_sel_hi:[1,0]
	v_rcp_f32_e32 v196, v196
	v_rcp_f32_e32 v197, v197
	v_rcp_f32_e32 v198, v198
	v_rcp_f32_e32 v199, v199
	v_pk_mul_f32 v[188:189], v[188:189], v[196:197]
	v_pk_mul_f32 v[190:191], v[190:191], v[198:199]
	v_pk_mul_f32 v[188:189], v[188:189], v[192:193]
	v_pk_mul_f32 v[190:191], v[190:191], v[194:195]
	v_cvt_pk_bf16_f32 v116, v188, v189
	v_cvt_pk_bf16_f32 v117, v190, v191
	v_add_u32_e32 v213, 0x134000, v215
	global_store_dwordx4 v213, v[114:117], s[96:97] nt
	s_branch .LBB0_359

.Lst_out_s8:
	s_lshl_b32 s8, s0, 8
	s_add_i32 s8, s8, s58
	s_lshl_b32 s9, s1, 7
	s_add_i32 s9, s9, s53
	s_lshl_b32 s10, s0, 3
	s_lshr_b32 s11, s58, 5
	s_add_i32 s10, s10, s11
	v_add_u32_e32 v200, s8, v163
	v_lshlrev_b32_e32 v213, 2, v200
	v_lshrrev_b32_e32 v212, 6, v222
	v_lshlrev_b32_e32 v109, 10, v212
	v_lshl_add_u32 v109, v225, 5, v109
	v_add_u32_e32 v109, 0x21040, v109
	v_lshlrev_b32_e32 v212, 9, v212
	v_lshl_add_u32 v212, v163, 2, v212
	v_add_u32_e32 v212, 0x20040, v212
	s_cmp_eq_u32 s52, 1
	s_cbranch_scc0 .Lfs8_ready
	v_lshl_add_u32 v201, v225, 3, s9
	v_lshlrev_b32_e32 v215, 2, v201
	global_load_dword v188, v213, s[4:5]
	global_load_dword v189, v213, s[4:5] offset:64
	global_load_dword v190, v213, s[4:5] offset:128
	global_load_dword v191, v213, s[4:5] offset:192
	global_load_dword v192, v213, s[4:5] offset:256
	global_load_dword v193, v213, s[4:5] offset:320
	global_load_dword v194, v213, s[4:5] offset:384
	global_load_dword v195, v213, s[4:5] offset:448
	v_add_u32_e32 v217, 0x21000, v215
	global_load_dwordx4 v[76:79], v217, s[82:83]
	v_add_u32_e32 v217, 0x2c000, v215
	global_load_dwordx4 v[80:83], v217, s[82:83]
	v_add_u32_e32 v217, 0x37000, v215
	global_load_dwordx4 v[84:87], v217, s[82:83]
	v_add_u32_e32 v217, 0xb000, v215
	global_load_dwordx4 v[88:91], v217, s[84:85]
	v_add_u32_e32 v217, 0x26800, v215
	global_load_dwordx4 v[92:95], v217, s[82:83]
	v_add_u32_e32 v217, 0x31800, v215
	global_load_dwordx4 v[96:99], v217, s[82:83]
	v_add_u32_e32 v217, 0x3c800, v215
	global_load_dwordx4 v[100:103], v217, s[82:83]
	v_add_u32_e32 v217, 0x10800, v215
	global_load_dwordx4 v[104:107], v217, s[84:85]
	s_waitcnt vmcnt(8)
	ds_write_b32 v212, v188
	ds_write_b32 v212, v189 offset:64
	ds_write_b32 v212, v190 offset:128
	ds_write_b32 v212, v191 offset:192
	ds_write_b32 v212, v192 offset:256
	ds_write_b32 v212, v193 offset:320
	ds_write_b32 v212, v194 offset:384
	ds_write_b32 v212, v195 offset:448
	s_waitcnt vmcnt(0)
	ds_write_b128 v109, v[76:79]
	ds_write_b128 v109, v[80:83] offset:128
	ds_write_b128 v109, v[84:87] offset:256
	ds_write_b128 v109, v[88:91] offset:384
	ds_write_b128 v109, v[92:95] offset:512
	ds_write_b128 v109, v[96:99] offset:640
	ds_write_b128 v109, v[100:103] offset:768
	ds_write_b128 v109, v[104:107] offset:896
	s_waitcnt lgkmcnt(0)
	v_add_u32_e32 v217, 0x21000, v215
	global_load_dwordx4 v[76:79], v217, s[82:83] offset:16
	v_add_u32_e32 v217, 0x2c000, v215
	global_load_dwordx4 v[80:83], v217, s[82:83] offset:16
	v_add_u32_e32 v217, 0x37000, v215
	global_load_dwordx4 v[84:87], v217, s[82:83] offset:16
	v_add_u32_e32 v217, 0xb000, v215
	global_load_dwordx4 v[88:91], v217, s[84:85] offset:16
	v_add_u32_e32 v217, 0x26800, v215
	global_load_dwordx4 v[92:95], v217, s[82:83] offset:16
	v_add_u32_e32 v217, 0x31800, v215
	global_load_dwordx4 v[96:99], v217, s[82:83] offset:16
	v_add_u32_e32 v217, 0x3c800, v215
	global_load_dwordx4 v[100:103], v217, s[82:83] offset:16
	v_add_u32_e32 v217, 0x10800, v215
	global_load_dwordx4 v[104:107], v217, s[84:85] offset:16
	s_waitcnt vmcnt(0)
	ds_write_b128 v109, v[76:79] offset:16
	ds_write_b128 v109, v[80:83] offset:144
	ds_write_b128 v109, v[84:87] offset:272
	ds_write_b128 v109, v[88:91] offset:400
	ds_write_b128 v109, v[92:95] offset:528
	ds_write_b128 v109, v[96:99] offset:656
	ds_write_b128 v109, v[100:103] offset:784
	ds_write_b128 v109, v[104:107] offset:912
	s_waitcnt lgkmcnt(0)
.Lfs8_ready:
	ds_read_b32 v188, v212
	ds_read_b32 v189, v212 offset:64
	ds_read_b32 v190, v212 offset:128
	ds_read_b32 v191, v212 offset:192
	ds_read_b32 v192, v212 offset:256
	ds_read_b32 v193, v212 offset:320
	ds_read_b32 v194, v212 offset:384
	ds_read_b32 v195, v212 offset:448
	ds_read_b128 v[76:79], v109
	ds_read_b128 v[80:83], v109 offset:128
	ds_read_b128 v[84:87], v109 offset:256
	ds_read_b128 v[88:91], v109 offset:384
	ds_read_b128 v[92:95], v109 offset:512
	ds_read_b128 v[96:99], v109 offset:640
	ds_read_b128 v[100:103], v109 offset:768
	ds_read_b128 v[104:107], v109 offset:896
	v_lshl_add_u32 v201, v225, 3, s9
	v_lshlrev_b32_e32 v212, 2, v201
	v_mul_u32_u24_e32 v215, 0x2c00, v200
	v_lshl_add_u32 v215, v201, 1, v215
	v_add_u32_e32 v213, s10, v163
	v_mul_u32_u24_e32 v217, 0xb000, v213
	v_add_u32_e32 v217, v217, v212
	v_cmp_gt_u32_e64 s[8:9], 2, v163
	v_cmp_lt_u32_e64 s[10:11], 13, v163
	v_cmp_lt_u32_e32 vcc, 1, v163
	v_mov_b32_e32 v214, 1.0
	v_mov_b32_e32 v216, 0xbfb8aa3b
	v_mov_b32_e32 v108, 0x3727c5ac
	s_waitcnt lgkmcnt(8)
	v_fmamk_f32 v188, v188, 0x3a000000, v108
	v_fmamk_f32 v189, v189, 0x3a000000, v108
	v_fmamk_f32 v190, v190, 0x3a000000, v108
	v_fmamk_f32 v191, v191, 0x3a000000, v108
	v_fmamk_f32 v192, v192, 0x3a000000, v108
	v_fmamk_f32 v193, v193, 0x3a000000, v108
	v_fmamk_f32 v194, v194, 0x3a000000, v108
	v_fmamk_f32 v195, v195, 0x3a000000, v108
	v_rsq_f32_e32 v188, v188
	v_rsq_f32_e32 v189, v189
	v_rsq_f32_e32 v190, v190
	v_rsq_f32_e32 v191, v191
	v_rsq_f32_e32 v192, v192
	v_rsq_f32_e32 v193, v193
	v_rsq_f32_e32 v194, v194
	v_rsq_f32_e32 v195, v195
	v_pk_mul_f32 v[158:159], v[158:159], v[188:189] op_sel_hi:[1,0]
	v_pk_mul_f32 v[160:161], v[160:161], v[188:189] op_sel_hi:[1,0]
	v_pk_mul_f32 v[60:61], v[60:61], v[188:189] op_sel_hi:[1,0]
	v_pk_mul_f32 v[62:63], v[62:63], v[188:189] op_sel_hi:[1,0]
	v_pk_mul_f32 v[154:155], v[154:155], v[188:189] op_sel_hi:[1,0]
	v_pk_mul_f32 v[156:157], v[156:157], v[188:189] op_sel_hi:[1,0]
	v_pk_mul_f32 v[56:57], v[56:57], v[188:189] op_sel_hi:[1,0]
	v_pk_mul_f32 v[58:59], v[58:59], v[188:189] op_sel_hi:[1,0]
	v_pk_mul_f32 v[150:151], v[150:151], v[188:189] op_sel:[0,1] op_sel_hi:[1,1]
	v_pk_mul_f32 v[152:153], v[152:153], v[188:189] op_sel:[0,1] op_sel_hi:[1,1]
	v_pk_mul_f32 v[52:53], v[52:53], v[188:189] op_sel:[0,1] op_sel_hi:[1,1]
	v_pk_mul_f32 v[54:55], v[54:55], v[188:189] op_sel:[0,1] op_sel_hi:[1,1]
	v_pk_mul_f32 v[142:143], v[142:143], v[188:189] op_sel:[0,1] op_sel_hi:[1,1]
	v_pk_mul_f32 v[144:145], v[144:145], v[188:189] op_sel:[0,1] op_sel_hi:[1,1]
	v_pk_mul_f32 v[44:45], v[44:45], v[188:189] op_sel:[0,1] op_sel_hi:[1,1]
	v_pk_mul_f32 v[46:47], v[46:47], v[188:189] op_sel:[0,1] op_sel_hi:[1,1]
	v_pk_mul_f32 v[146:147], v[146:147], v[190:191] op_sel_hi:[1,0]
	v_pk_mul_f32 v[148:149], v[148:149], v[190:191] op_sel_hi:[1,0]
	v_pk_mul_f32 v[48:49], v[48:49], v[190:191] op_sel_hi:[1,0]
	v_pk_mul_f32 v[50:51], v[50:51], v[190:191] op_sel_hi:[1,0]
	v_pk_mul_f32 v[134:135], v[134:135], v[190:191] op_sel_hi:[1,0]
	v_pk_mul_f32 v[136:137], v[136:137], v[190:191] op_sel_hi:[1,0]
	v_pk_mul_f32 v[36:37], v[36:37], v[190:191] op_sel_hi:[1,0]
	v_pk_mul_f32 v[38:39], v[38:39], v[190:191] op_sel_hi:[1,0]
	v_pk_mul_f32 v[138:139], v[138:139], v[190:191] op_sel:[0,1] op_sel_hi:[1,1]
	v_pk_mul_f32 v[140:141], v[140:141], v[190:191] op_sel:[0,1] op_sel_hi:[1,1]
	v_pk_mul_f32 v[40:41], v[40:41], v[190:191] op_sel:[0,1] op_sel_hi:[1,1]
	v_pk_mul_f32 v[42:43], v[42:43], v[190:191] op_sel:[0,1] op_sel_hi:[1,1]
	v_pk_mul_f32 v[130:131], v[130:131], v[190:191] op_sel:[0,1] op_sel_hi:[1,1]
	v_pk_mul_f32 v[132:133], v[132:133], v[190:191] op_sel:[0,1] op_sel_hi:[1,1]
	v_pk_mul_f32 v[32:33], v[32:33], v[190:191] op_sel:[0,1] op_sel_hi:[1,1]
	v_pk_mul_f32 v[34:35], v[34:35], v[190:191] op_sel:[0,1] op_sel_hi:[1,1]
	v_pk_mul_f32 v[126:127], v[126:127], v[192:193] op_sel_hi:[1,0]
	v_pk_mul_f32 v[128:129], v[128:129], v[192:193] op_sel_hi:[1,0]
	v_pk_mul_f32 v[28:29], v[28:29], v[192:193] op_sel_hi:[1,0]
	v_pk_mul_f32 v[30:31], v[30:31], v[192:193] op_sel_hi:[1,0]
	v_pk_mul_f32 v[118:119], v[118:119], v[192:193] op_sel_hi:[1,0]
	v_pk_mul_f32 v[120:121], v[120:121], v[192:193] op_sel_hi:[1,0]
	v_pk_mul_f32 v[16:17], v[16:17], v[192:193] op_sel_hi:[1,0]
	v_pk_mul_f32 v[18:19], v[18:19], v[192:193] op_sel_hi:[1,0]
	v_pk_mul_f32 v[122:123], v[122:123], v[192:193] op_sel:[0,1] op_sel_hi:[1,1]
	v_pk_mul_f32 v[124:125], v[124:125], v[192:193] op_sel:[0,1] op_sel_hi:[1,1]
	v_pk_mul_f32 v[24:25], v[24:25], v[192:193] op_sel:[0,1] op_sel_hi:[1,1]
	v_pk_mul_f32 v[26:27], v[26:27], v[192:193] op_sel:[0,1] op_sel_hi:[1,1]
	v_pk_mul_f32 v[110:111], v[110:111], v[192:193] op_sel:[0,1] op_sel_hi:[1,1]
	v_pk_mul_f32 v[112:113], v[112:113], v[192:193] op_sel:[0,1] op_sel_hi:[1,1]
	v_pk_mul_f32 v[12:13], v[12:13], v[192:193] op_sel:[0,1] op_sel_hi:[1,1]
	v_pk_mul_f32 v[14:15], v[14:15], v[192:193] op_sel:[0,1] op_sel_hi:[1,1]
	v_pk_mul_f32 v[114:115], v[114:115], v[194:195] op_sel_hi:[1,0]
	v_pk_mul_f32 v[116:117], v[116:117], v[194:195] op_sel_hi:[1,0]
	v_pk_mul_f32 v[20:21], v[20:21], v[194:195] op_sel_hi:[1,0]
	v_pk_mul_f32 v[22:23], v[22:23], v[194:195] op_sel_hi:[1,0]
	v_pk_mul_f32 v[68:69], v[68:69], v[194:195] op_sel_hi:[1,0]
	v_pk_mul_f32 v[70:71], v[70:71], v[194:195] op_sel_hi:[1,0]
	v_pk_mul_f32 v[8:9], v[8:9], v[194:195] op_sel_hi:[1,0]
	v_pk_mul_f32 v[10:11], v[10:11], v[194:195] op_sel_hi:[1,0]
	v_pk_mul_f32 v[72:73], v[72:73], v[194:195] op_sel:[0,1] op_sel_hi:[1,1]
	v_pk_mul_f32 v[74:75], v[74:75], v[194:195] op_sel:[0,1] op_sel_hi:[1,1]
	v_pk_mul_f32 v[4:5], v[4:5], v[194:195] op_sel:[0,1] op_sel_hi:[1,1]
	v_pk_mul_f32 v[6:7], v[6:7], v[194:195] op_sel:[0,1] op_sel_hi:[1,1]
	v_pk_mul_f32 v[64:65], v[64:65], v[194:195] op_sel:[0,1] op_sel_hi:[1,1]
	v_pk_mul_f32 v[66:67], v[66:67], v[194:195] op_sel:[0,1] op_sel_hi:[1,1]
	v_pk_mul_f32 v[0:1], v[0:1], v[194:195] op_sel:[0,1] op_sel_hi:[1,1]
	v_pk_mul_f32 v[2:3], v[2:3], v[194:195] op_sel:[0,1] op_sel_hi:[1,1]
	s_nop 1
	s_mov_b64 exec, s[8:9]
	v_add_u32_e32 v213, 0x5800, v217
	global_store_dwordx4 v217, v[158:161], s[70:71]
	global_store_dwordx4 v213, v[154:157], s[70:71]
	global_store_dwordx4 v217, v[60:63], s[70:71] offset:16
	global_store_dwordx4 v213, v[56:59], s[70:71] offset:16
	s_mov_b64 exec, s[10:11]
	v_add_u32_e32 v213, 0xfff7c000, v217
	global_store_dwordx4 v213, v[72:75], s[70:71]
	global_store_dwordx4 v213, v[4:7], s[70:71] offset:16
	v_add_u32_e32 v213, 0xfff81800, v217
	global_store_dwordx4 v213, v[64:67], s[70:71]
	global_store_dwordx4 v213, v[0:3], s[70:71] offset:16
	s_mov_b64 exec, -1
	v_cmp_eq_u32_e64 s[8:9], 15, v163
	ds_read_b128 v[204:207], v109 offset:784
	ds_read_b128 v[208:211], v109 offset:912
	s_waitcnt lgkmcnt(0)
	v_pk_fma_f32 v[188:189], v[158:159], v[84:85], v[88:89]
	v_pk_fma_f32 v[190:191], v[160:161], v[86:87], v[90:91]
	v_pk_fma_f32 v[192:193], v[154:155], v[100:101], v[104:105]
	v_pk_fma_f32 v[194:195], v[156:157], v[102:103], v[106:107]
	v_fmac_f32_dpp v188, v158, v80 row_shr:1 row_mask:0xf bank_mask:0xf
	v_fmac_f32_dpp v189, v159, v81 row_shr:1 row_mask:0xf bank_mask:0xf
	v_fmac_f32_dpp v190, v160, v82 row_shr:1 row_mask:0xf bank_mask:0xf
	v_fmac_f32_dpp v191, v161, v83 row_shr:1 row_mask:0xf bank_mask:0xf
	v_fmac_f32_dpp v192, v154, v96 row_shr:1 row_mask:0xf bank_mask:0xf
	v_fmac_f32_dpp v193, v155, v97 row_shr:1 row_mask:0xf bank_mask:0xf
	v_fmac_f32_dpp v194, v156, v98 row_shr:1 row_mask:0xf bank_mask:0xf
	v_fmac_f32_dpp v195, v157, v99 row_shr:1 row_mask:0xf bank_mask:0xf
	v_fmac_f32_dpp v188, v158, v76 row_shr:2 row_mask:0xf bank_mask:0xf
	v_fmac_f32_dpp v189, v159, v77 row_shr:2 row_mask:0xf bank_mask:0xf
	v_fmac_f32_dpp v190, v160, v78 row_shr:2 row_mask:0xf bank_mask:0xf
	v_fmac_f32_dpp v191, v161, v79 row_shr:2 row_mask:0xf bank_mask:0xf
	v_fmac_f32_dpp v192, v154, v92 row_shr:2 row_mask:0xf bank_mask:0xf
	v_fmac_f32_dpp v193, v155, v93 row_shr:2 row_mask:0xf bank_mask:0xf
	v_fmac_f32_dpp v194, v156, v94 row_shr:2 row_mask:0xf bank_mask:0xf
	v_fmac_f32_dpp v195, v157, v95 row_shr:2 row_mask:0xf bank_mask:0xf
	v_pk_mul_f32 v[196:197], v[188:189], v[216:217] op_sel_hi:[1,0]
	v_pk_mul_f32 v[198:199], v[190:191], v[216:217] op_sel_hi:[1,0]
	v_exp_f32_e32 v196, v196
	v_exp_f32_e32 v197, v197
	v_exp_f32_e32 v198, v198
	v_exp_f32_e32 v199, v199
	v_pk_add_f32 v[196:197], v[196:197], v[214:215] op_sel_hi:[1,0]
	v_pk_add_f32 v[198:199], v[198:199], v[214:215] op_sel_hi:[1,0]
	v_rcp_f32_e32 v196, v196
	v_rcp_f32_e32 v197, v197
	v_rcp_f32_e32 v198, v198
	v_rcp_f32_e32 v199, v199
	v_pk_mul_f32 v[188:189], v[188:189], v[196:197]
	v_pk_mul_f32 v[190:191], v[190:191], v[198:199]
	v_pk_mul_f32 v[188:189], v[188:189], v[192:193]
	v_pk_mul_f32 v[190:191], v[190:191], v[194:195]
	v_cvt_pk_bf16_f32 v200, v188, v189
	v_cvt_pk_bf16_f32 v201, v190, v191
	v_pk_fma_f32 v[188:189], v[150:151], v[84:85], v[88:89]
	v_pk_fma_f32 v[190:191], v[152:153], v[86:87], v[90:91]
	v_pk_fma_f32 v[192:193], v[142:143], v[100:101], v[104:105]
	v_pk_fma_f32 v[194:195], v[144:145], v[102:103], v[106:107]
	v_cndmask_b32_e64 v158, v150, v158, s[10:11]
	v_cndmask_b32_e64 v159, v151, v159, s[10:11]
	v_cndmask_b32_e64 v160, v152, v160, s[10:11]
	v_cndmask_b32_e64 v161, v153, v161, s[10:11]
	v_cndmask_b32_e64 v154, v142, v154, s[10:11]
	v_cndmask_b32_e64 v155, v143, v155, s[10:11]
	v_cndmask_b32_e64 v156, v144, v156, s[10:11]
	v_cndmask_b32_e64 v157, v145, v157, s[10:11]
	v_fmac_f32_dpp v188, v158, v76 row_ror:2 row_mask:0xf bank_mask:0xf
	v_fmac_f32_dpp v189, v159, v77 row_ror:2 row_mask:0xf bank_mask:0xf
	v_fmac_f32_dpp v190, v160, v78 row_ror:2 row_mask:0xf bank_mask:0xf
	v_fmac_f32_dpp v191, v161, v79 row_ror:2 row_mask:0xf bank_mask:0xf
	v_fmac_f32_dpp v192, v154, v92 row_ror:2 row_mask:0xf bank_mask:0xf
	v_fmac_f32_dpp v193, v155, v93 row_ror:2 row_mask:0xf bank_mask:0xf
	v_fmac_f32_dpp v194, v156, v94 row_ror:2 row_mask:0xf bank_mask:0xf
	v_fmac_f32_dpp v195, v157, v95 row_ror:2 row_mask:0xf bank_mask:0xf
	v_cndmask_b32_e64 v158, v150, v158, s[8:9]
	v_cndmask_b32_e64 v159, v151, v159, s[8:9]
	v_cndmask_b32_e64 v160, v152, v160, s[8:9]
	v_cndmask_b32_e64 v161, v153, v161, s[8:9]
	v_cndmask_b32_e64 v154, v142, v154, s[8:9]
	v_cndmask_b32_e64 v155, v143, v155, s[8:9]
	v_cndmask_b32_e64 v156, v144, v156, s[8:9]
	v_cndmask_b32_e64 v157, v145, v157, s[8:9]
	v_fmac_f32_dpp v188, v158, v80 row_ror:1 row_mask:0xf bank_mask:0xf
	v_fmac_f32_dpp v189, v159, v81 row_ror:1 row_mask:0xf bank_mask:0xf
	v_fmac_f32_dpp v190, v160, v82 row_ror:1 row_mask:0xf bank_mask:0xf
	v_fmac_f32_dpp v191, v161, v83 row_ror:1 row_mask:0xf bank_mask:0xf
	v_fmac_f32_dpp v192, v154, v96 row_ror:1 row_mask:0xf bank_mask:0xf
	v_fmac_f32_dpp v193, v155, v97 row_ror:1 row_mask:0xf bank_mask:0xf
	v_fmac_f32_dpp v194, v156, v98 row_ror:1 row_mask:0xf bank_mask:0xf
	v_fmac_f32_dpp v195, v157, v99 row_ror:1 row_mask:0xf bank_mask:0xf
	v_pk_mul_f32 v[196:197], v[188:189], v[216:217] op_sel_hi:[1,0]
	v_pk_mul_f32 v[198:199], v[190:191], v[216:217] op_sel_hi:[1,0]
	v_exp_f32_e32 v196, v196
	v_exp_f32_e32 v197, v197
	v_exp_f32_e32 v198, v198
	v_exp_f32_e32 v199, v199
	v_pk_add_f32 v[196:197], v[196:197], v[214:215] op_sel_hi:[1,0]
	v_pk_add_f32 v[198:199], v[198:199], v[214:215] op_sel_hi:[1,0]
	v_rcp_f32_e32 v196, v196
	v_rcp_f32_e32 v197, v197
	v_rcp_f32_e32 v198, v198
	v_rcp_f32_e32 v199, v199
	v_pk_mul_f32 v[188:189], v[188:189], v[196:197]
	v_pk_mul_f32 v[190:191], v[190:191], v[198:199]
	v_pk_mul_f32 v[188:189], v[188:189], v[192:193]
	v_pk_mul_f32 v[190:191], v[190:191], v[194:195]
	v_cvt_pk_bf16_f32 v158, v188, v189
	v_cvt_pk_bf16_f32 v159, v190, v191
	ds_read_b128 v[154:157], v109 offset:16
	v_pk_fma_f32 v[188:189], v[146:147], v[84:85], v[88:89]
	v_pk_fma_f32 v[190:191], v[148:149], v[86:87], v[90:91]
	v_pk_fma_f32 v[192:193], v[134:135], v[100:101], v[104:105]
	v_pk_fma_f32 v[194:195], v[136:137], v[102:103], v[106:107]
	v_cndmask_b32_e64 v150, v146, v150, s[10:11]
	v_cndmask_b32_e64 v151, v147, v151, s[10:11]
	v_cndmask_b32_e64 v152, v148, v152, s[10:11]
	v_cndmask_b32_e64 v153, v149, v153, s[10:11]
	v_cndmask_b32_e64 v142, v134, v142, s[10:11]
	v_cndmask_b32_e64 v143, v135, v143, s[10:11]
	v_cndmask_b32_e64 v144, v136, v144, s[10:11]
	v_cndmask_b32_e64 v145, v137, v145, s[10:11]
	v_fmac_f32_dpp v188, v150, v76 row_ror:2 row_mask:0xf bank_mask:0xf
	v_fmac_f32_dpp v189, v151, v77 row_ror:2 row_mask:0xf bank_mask:0xf
	v_fmac_f32_dpp v190, v152, v78 row_ror:2 row_mask:0xf bank_mask:0xf
	v_fmac_f32_dpp v191, v153, v79 row_ror:2 row_mask:0xf bank_mask:0xf
	v_fmac_f32_dpp v192, v142, v92 row_ror:2 row_mask:0xf bank_mask:0xf
	v_fmac_f32_dpp v193, v143, v93 row_ror:2 row_mask:0xf bank_mask:0xf
	v_fmac_f32_dpp v194, v144, v94 row_ror:2 row_mask:0xf bank_mask:0xf
	v_fmac_f32_dpp v195, v145, v95 row_ror:2 row_mask:0xf bank_mask:0xf
	v_cndmask_b32_e64 v150, v146, v150, s[8:9]
	v_cndmask_b32_e64 v151, v147, v151, s[8:9]
	v_cndmask_b32_e64 v152, v148, v152, s[8:9]
	v_cndmask_b32_e64 v153, v149, v153, s[8:9]
	v_cndmask_b32_e64 v142, v134, v142, s[8:9]
	v_cndmask_b32_e64 v143, v135, v143, s[8:9]
	v_cndmask_b32_e64 v144, v136, v144, s[8:9]
	v_cndmask_b32_e64 v145, v137, v145, s[8:9]
	v_fmac_f32_dpp v188, v150, v80 row_ror:1 row_mask:0xf bank_mask:0xf
	v_fmac_f32_dpp v189, v151, v81 row_ror:1 row_mask:0xf bank_mask:0xf
	v_fmac_f32_dpp v190, v152, v82 row_ror:1 row_mask:0xf bank_mask:0xf
	v_fmac_f32_dpp v191, v153, v83 row_ror:1 row_mask:0xf bank_mask:0xf
	v_fmac_f32_dpp v192, v142, v96 row_ror:1 row_mask:0xf bank_mask:0xf
	v_fmac_f32_dpp v193, v143, v97 row_ror:1 row_mask:0xf bank_mask:0xf
	v_fmac_f32_dpp v194, v144, v98 row_ror:1 row_mask:0xf bank_mask:0xf
	v_fmac_f32_dpp v195, v145, v99 row_ror:1 row_mask:0xf bank_mask:0xf
	v_pk_mul_f32 v[196:197], v[188:189], v[216:217] op_sel_hi:[1,0]
	v_pk_mul_f32 v[198:199], v[190:191], v[216:217] op_sel_hi:[1,0]
	v_exp_f32_e32 v196, v196
	v_exp_f32_e32 v197, v197
	v_exp_f32_e32 v198, v198
	v_exp_f32_e32 v199, v199
	v_pk_add_f32 v[196:197], v[196:197], v[214:215] op_sel_hi:[1,0]
	v_pk_add_f32 v[198:199], v[198:199], v[214:215] op_sel_hi:[1,0]
	v_rcp_f32_e32 v196, v196
	v_rcp_f32_e32 v197, v197
	v_rcp_f32_e32 v198, v198
	v_rcp_f32_e32 v199, v199
	v_pk_mul_f32 v[188:189], v[188:189], v[196:197]
	v_pk_mul_f32 v[190:191], v[190:191], v[198:199]
	v_pk_mul_f32 v[188:189], v[188:189], v[192:193]
	v_pk_mul_f32 v[190:191], v[190:191], v[194:195]
	v_cvt_pk_bf16_f32 v150, v188, v189
	v_cvt_pk_bf16_f32 v151, v190, v191
	ds_read_b128 v[142:145], v109 offset:144
	v_pk_fma_f32 v[188:189], v[138:139], v[84:85], v[88:89]
	v_pk_fma_f32 v[190:191], v[140:141], v[86:87], v[90:91]
	v_pk_fma_f32 v[192:193], v[130:131], v[100:101], v[104:105]
	v_pk_fma_f32 v[194:195], v[132:133], v[102:103], v[106:107]
	v_cndmask_b32_e64 v146, v138, v146, s[10:11]
	v_cndmask_b32_e64 v147, v139, v147, s[10:11]
	v_cndmask_b32_e64 v148, v140, v148, s[10:11]
	v_cndmask_b32_e64 v149, v141, v149, s[10:11]
	v_cndmask_b32_e64 v134, v130, v134, s[10:11]
	v_cndmask_b32_e64 v135, v131, v135, s[10:11]
	v_cndmask_b32_e64 v136, v132, v136, s[10:11]
	v_cndmask_b32_e64 v137, v133, v137, s[10:11]
	v_fmac_f32_dpp v188, v146, v76 row_ror:2 row_mask:0xf bank_mask:0xf
	v_fmac_f32_dpp v189, v147, v77 row_ror:2 row_mask:0xf bank_mask:0xf
	v_fmac_f32_dpp v190, v148, v78 row_ror:2 row_mask:0xf bank_mask:0xf
	v_fmac_f32_dpp v191, v149, v79 row_ror:2 row_mask:0xf bank_mask:0xf
	v_fmac_f32_dpp v192, v134, v92 row_ror:2 row_mask:0xf bank_mask:0xf
	v_fmac_f32_dpp v193, v135, v93 row_ror:2 row_mask:0xf bank_mask:0xf
	v_fmac_f32_dpp v194, v136, v94 row_ror:2 row_mask:0xf bank_mask:0xf
	v_fmac_f32_dpp v195, v137, v95 row_ror:2 row_mask:0xf bank_mask:0xf
	v_cndmask_b32_e64 v146, v138, v146, s[8:9]
	v_cndmask_b32_e64 v147, v139, v147, s[8:9]
	v_cndmask_b32_e64 v148, v140, v148, s[8:9]
	v_cndmask_b32_e64 v149, v141, v149, s[8:9]
	v_cndmask_b32_e64 v134, v130, v134, s[8:9]
	v_cndmask_b32_e64 v135, v131, v135, s[8:9]
	v_cndmask_b32_e64 v136, v132, v136, s[8:9]
	v_cndmask_b32_e64 v137, v133, v137, s[8:9]
	v_fmac_f32_dpp v188, v146, v80 row_ror:1 row_mask:0xf bank_mask:0xf
	v_fmac_f32_dpp v189, v147, v81 row_ror:1 row_mask:0xf bank_mask:0xf
	v_fmac_f32_dpp v190, v148, v82 row_ror:1 row_mask:0xf bank_mask:0xf
	v_fmac_f32_dpp v191, v149, v83 row_ror:1 row_mask:0xf bank_mask:0xf
	v_fmac_f32_dpp v192, v134, v96 row_ror:1 row_mask:0xf bank_mask:0xf
	v_fmac_f32_dpp v193, v135, v97 row_ror:1 row_mask:0xf bank_mask:0xf
	v_fmac_f32_dpp v194, v136, v98 row_ror:1 row_mask:0xf bank_mask:0xf
	v_fmac_f32_dpp v195, v137, v99 row_ror:1 row_mask:0xf bank_mask:0xf
	v_pk_mul_f32 v[196:197], v[188:189], v[216:217] op_sel_hi:[1,0]
	v_pk_mul_f32 v[198:199], v[190:191], v[216:217] op_sel_hi:[1,0]
	v_exp_f32_e32 v196, v196
	v_exp_f32_e32 v197, v197
	v_exp_f32_e32 v198, v198
	v_exp_f32_e32 v199, v199
	v_pk_add_f32 v[196:197], v[196:197], v[214:215] op_sel_hi:[1,0]
	v_pk_add_f32 v[198:199], v[198:199], v[214:215] op_sel_hi:[1,0]
	v_rcp_f32_e32 v196, v196
	v_rcp_f32_e32 v197, v197
	v_rcp_f32_e32 v198, v198
	v_rcp_f32_e32 v199, v199
	v_pk_mul_f32 v[188:189], v[188:189], v[196:197]
	v_pk_mul_f32 v[190:191], v[190:191], v[198:199]
	v_pk_mul_f32 v[188:189], v[188:189], v[192:193]
	v_pk_mul_f32 v[190:191], v[190:191], v[194:195]
	v_cvt_pk_bf16_f32 v146, v188, v189
	v_cvt_pk_bf16_f32 v147, v190, v191
	ds_read_b128 v[134:137], v109 offset:272
	v_pk_fma_f32 v[188:189], v[126:127], v[84:85], v[88:89]
	v_pk_fma_f32 v[190:191], v[128:129], v[86:87], v[90:91]
	v_pk_fma_f32 v[192:193], v[118:119], v[100:101], v[104:105]
	v_pk_fma_f32 v[194:195], v[120:121], v[102:103], v[106:107]
	v_cndmask_b32_e64 v138, v126, v138, s[10:11]
	v_cndmask_b32_e64 v139, v127, v139, s[10:11]
	v_cndmask_b32_e64 v140, v128, v140, s[10:11]
	v_cndmask_b32_e64 v141, v129, v141, s[10:11]
	v_cndmask_b32_e64 v130, v118, v130, s[10:11]
	v_cndmask_b32_e64 v131, v119, v131, s[10:11]
	v_cndmask_b32_e64 v132, v120, v132, s[10:11]
	v_cndmask_b32_e64 v133, v121, v133, s[10:11]
	v_fmac_f32_dpp v188, v138, v76 row_ror:2 row_mask:0xf bank_mask:0xf
	v_fmac_f32_dpp v189, v139, v77 row_ror:2 row_mask:0xf bank_mask:0xf
	v_fmac_f32_dpp v190, v140, v78 row_ror:2 row_mask:0xf bank_mask:0xf
	v_fmac_f32_dpp v191, v141, v79 row_ror:2 row_mask:0xf bank_mask:0xf
	v_fmac_f32_dpp v192, v130, v92 row_ror:2 row_mask:0xf bank_mask:0xf
	v_fmac_f32_dpp v193, v131, v93 row_ror:2 row_mask:0xf bank_mask:0xf
	v_fmac_f32_dpp v194, v132, v94 row_ror:2 row_mask:0xf bank_mask:0xf
	v_fmac_f32_dpp v195, v133, v95 row_ror:2 row_mask:0xf bank_mask:0xf
	v_cndmask_b32_e64 v138, v126, v138, s[8:9]
	v_cndmask_b32_e64 v139, v127, v139, s[8:9]
	v_cndmask_b32_e64 v140, v128, v140, s[8:9]
	v_cndmask_b32_e64 v141, v129, v141, s[8:9]
	v_cndmask_b32_e64 v130, v118, v130, s[8:9]
	v_cndmask_b32_e64 v131, v119, v131, s[8:9]
	v_cndmask_b32_e64 v132, v120, v132, s[8:9]
	v_cndmask_b32_e64 v133, v121, v133, s[8:9]
	v_fmac_f32_dpp v188, v138, v80 row_ror:1 row_mask:0xf bank_mask:0xf
	v_fmac_f32_dpp v189, v139, v81 row_ror:1 row_mask:0xf bank_mask:0xf
	v_fmac_f32_dpp v190, v140, v82 row_ror:1 row_mask:0xf bank_mask:0xf
	v_fmac_f32_dpp v191, v141, v83 row_ror:1 row_mask:0xf bank_mask:0xf
	v_fmac_f32_dpp v192, v130, v96 row_ror:1 row_mask:0xf bank_mask:0xf
	v_fmac_f32_dpp v193, v131, v97 row_ror:1 row_mask:0xf bank_mask:0xf
	v_fmac_f32_dpp v194, v132, v98 row_ror:1 row_mask:0xf bank_mask:0xf
	v_fmac_f32_dpp v195, v133, v99 row_ror:1 row_mask:0xf bank_mask:0xf
	v_pk_mul_f32 v[196:197], v[188:189], v[216:217] op_sel_hi:[1,0]
	v_pk_mul_f32 v[198:199], v[190:191], v[216:217] op_sel_hi:[1,0]
	v_exp_f32_e32 v196, v196
	v_exp_f32_e32 v197, v197
	v_exp_f32_e32 v198, v198
	v_exp_f32_e32 v199, v199
	v_pk_add_f32 v[196:197], v[196:197], v[214:215] op_sel_hi:[1,0]
	v_pk_add_f32 v[198:199], v[198:199], v[214:215] op_sel_hi:[1,0]
	v_rcp_f32_e32 v196, v196
	v_rcp_f32_e32 v197, v197
	v_rcp_f32_e32 v198, v198
	v_rcp_f32_e32 v199, v199
	v_pk_mul_f32 v[188:189], v[188:189], v[196:197]
	v_pk_mul_f32 v[190:191], v[190:191], v[198:199]
	v_pk_mul_f32 v[188:189], v[188:189], v[192:193]
	v_pk_mul_f32 v[190:191], v[190:191], v[194:195]
	v_cvt_pk_bf16_f32 v138, v188, v189
	v_cvt_pk_bf16_f32 v139, v190, v191
	ds_read_b128 v[130:133], v109 offset:400
	v_pk_fma_f32 v[188:189], v[122:123], v[84:85], v[88:89]
	v_pk_fma_f32 v[190:191], v[124:125], v[86:87], v[90:91]
	v_pk_fma_f32 v[192:193], v[110:111], v[100:101], v[104:105]
	v_pk_fma_f32 v[194:195], v[112:113], v[102:103], v[106:107]
	v_cndmask_b32_e64 v126, v122, v126, s[10:11]
	v_cndmask_b32_e64 v127, v123, v127, s[10:11]
	v_cndmask_b32_e64 v128, v124, v128, s[10:11]
	v_cndmask_b32_e64 v129, v125, v129, s[10:11]
	v_cndmask_b32_e64 v118, v110, v118, s[10:11]
	v_cndmask_b32_e64 v119, v111, v119, s[10:11]
	v_cndmask_b32_e64 v120, v112, v120, s[10:11]
	v_cndmask_b32_e64 v121, v113, v121, s[10:11]
	v_fmac_f32_dpp v188, v126, v76 row_ror:2 row_mask:0xf bank_mask:0xf
	v_fmac_f32_dpp v189, v127, v77 row_ror:2 row_mask:0xf bank_mask:0xf
	v_fmac_f32_dpp v190, v128, v78 row_ror:2 row_mask:0xf bank_mask:0xf
	v_fmac_f32_dpp v191, v129, v79 row_ror:2 row_mask:0xf bank_mask:0xf
	v_fmac_f32_dpp v192, v118, v92 row_ror:2 row_mask:0xf bank_mask:0xf
	v_fmac_f32_dpp v193, v119, v93 row_ror:2 row_mask:0xf bank_mask:0xf
	v_fmac_f32_dpp v194, v120, v94 row_ror:2 row_mask:0xf bank_mask:0xf
	v_fmac_f32_dpp v195, v121, v95 row_ror:2 row_mask:0xf bank_mask:0xf
	v_cndmask_b32_e64 v126, v122, v126, s[8:9]
	v_cndmask_b32_e64 v127, v123, v127, s[8:9]
	v_cndmask_b32_e64 v128, v124, v128, s[8:9]
	v_cndmask_b32_e64 v129, v125, v129, s[8:9]
	v_cndmask_b32_e64 v118, v110, v118, s[8:9]
	v_cndmask_b32_e64 v119, v111, v119, s[8:9]
	v_cndmask_b32_e64 v120, v112, v120, s[8:9]
	v_cndmask_b32_e64 v121, v113, v121, s[8:9]
	v_fmac_f32_dpp v188, v126, v80 row_ror:1 row_mask:0xf bank_mask:0xf
	v_fmac_f32_dpp v189, v127, v81 row_ror:1 row_mask:0xf bank_mask:0xf
	v_fmac_f32_dpp v190, v128, v82 row_ror:1 row_mask:0xf bank_mask:0xf
	v_fmac_f32_dpp v191, v129, v83 row_ror:1 row_mask:0xf bank_mask:0xf
	v_fmac_f32_dpp v192, v118, v96 row_ror:1 row_mask:0xf bank_mask:0xf
	v_fmac_f32_dpp v193, v119, v97 row_ror:1 row_mask:0xf bank_mask:0xf
	v_fmac_f32_dpp v194, v120, v98 row_ror:1 row_mask:0xf bank_mask:0xf
	v_fmac_f32_dpp v195, v121, v99 row_ror:1 row_mask:0xf bank_mask:0xf
	v_pk_mul_f32 v[196:197], v[188:189], v[216:217] op_sel_hi:[1,0]
	v_pk_mul_f32 v[198:199], v[190:191], v[216:217] op_sel_hi:[1,0]
	v_exp_f32_e32 v196, v196
	v_exp_f32_e32 v197, v197
	v_exp_f32_e32 v198, v198
	v_exp_f32_e32 v199, v199
	v_pk_add_f32 v[196:197], v[196:197], v[214:215] op_sel_hi:[1,0]
	v_pk_add_f32 v[198:199], v[198:199], v[214:215] op_sel_hi:[1,0]
	v_rcp_f32_e32 v196, v196
	v_rcp_f32_e32 v197, v197
	v_rcp_f32_e32 v198, v198
	v_rcp_f32_e32 v199, v199
	v_pk_mul_f32 v[188:189], v[188:189], v[196:197]
	v_pk_mul_f32 v[190:191], v[190:191], v[198:199]
	v_pk_mul_f32 v[188:189], v[188:189], v[192:193]
	v_pk_mul_f32 v[190:191], v[190:191], v[194:195]
	v_cvt_pk_bf16_f32 v126, v188, v189
	v_cvt_pk_bf16_f32 v127, v190, v191
	ds_read_b128 v[118:121], v109 offset:528
	v_pk_fma_f32 v[188:189], v[114:115], v[84:85], v[88:89]
	v_pk_fma_f32 v[190:191], v[116:117], v[86:87], v[90:91]
	v_pk_fma_f32 v[192:193], v[68:69], v[100:101], v[104:105]
	v_pk_fma_f32 v[194:195], v[70:71], v[102:103], v[106:107]
	v_cndmask_b32_e64 v122, v114, v122, s[10:11]
	v_cndmask_b32_e64 v123, v115, v123, s[10:11]
	v_cndmask_b32_e64 v124, v116, v124, s[10:11]
	v_cndmask_b32_e64 v125, v117, v125, s[10:11]
	v_cndmask_b32_e64 v110, v68, v110, s[10:11]
	v_cndmask_b32_e64 v111, v69, v111, s[10:11]
	v_cndmask_b32_e64 v112, v70, v112, s[10:11]
	v_cndmask_b32_e64 v113, v71, v113, s[10:11]
	v_fmac_f32_dpp v188, v122, v76 row_ror:2 row_mask:0xf bank_mask:0xf
	v_fmac_f32_dpp v189, v123, v77 row_ror:2 row_mask:0xf bank_mask:0xf
	v_fmac_f32_dpp v190, v124, v78 row_ror:2 row_mask:0xf bank_mask:0xf
	v_fmac_f32_dpp v191, v125, v79 row_ror:2 row_mask:0xf bank_mask:0xf
	v_fmac_f32_dpp v192, v110, v92 row_ror:2 row_mask:0xf bank_mask:0xf
	v_fmac_f32_dpp v193, v111, v93 row_ror:2 row_mask:0xf bank_mask:0xf
	v_fmac_f32_dpp v194, v112, v94 row_ror:2 row_mask:0xf bank_mask:0xf
	v_fmac_f32_dpp v195, v113, v95 row_ror:2 row_mask:0xf bank_mask:0xf
	v_cndmask_b32_e64 v122, v114, v122, s[8:9]
	v_cndmask_b32_e64 v123, v115, v123, s[8:9]
	v_cndmask_b32_e64 v124, v116, v124, s[8:9]
	v_cndmask_b32_e64 v125, v117, v125, s[8:9]
	v_cndmask_b32_e64 v110, v68, v110, s[8:9]
	v_cndmask_b32_e64 v111, v69, v111, s[8:9]
	v_cndmask_b32_e64 v112, v70, v112, s[8:9]
	v_cndmask_b32_e64 v113, v71, v113, s[8:9]
	v_fmac_f32_dpp v188, v122, v80 row_ror:1 row_mask:0xf bank_mask:0xf
	v_fmac_f32_dpp v189, v123, v81 row_ror:1 row_mask:0xf bank_mask:0xf
	v_fmac_f32_dpp v190, v124, v82 row_ror:1 row_mask:0xf bank_mask:0xf
	v_fmac_f32_dpp v191, v125, v83 row_ror:1 row_mask:0xf bank_mask:0xf
	v_fmac_f32_dpp v192, v110, v96 row_ror:1 row_mask:0xf bank_mask:0xf
	v_fmac_f32_dpp v193, v111, v97 row_ror:1 row_mask:0xf bank_mask:0xf
	v_fmac_f32_dpp v194, v112, v98 row_ror:1 row_mask:0xf bank_mask:0xf
	v_fmac_f32_dpp v195, v113, v99 row_ror:1 row_mask:0xf bank_mask:0xf
	v_pk_mul_f32 v[196:197], v[188:189], v[216:217] op_sel_hi:[1,0]
	v_pk_mul_f32 v[198:199], v[190:191], v[216:217] op_sel_hi:[1,0]
	v_exp_f32_e32 v196, v196
	v_exp_f32_e32 v197, v197
	v_exp_f32_e32 v198, v198
	v_exp_f32_e32 v199, v199
	v_pk_add_f32 v[196:197], v[196:197], v[214:215] op_sel_hi:[1,0]
	v_pk_add_f32 v[198:199], v[198:199], v[214:215] op_sel_hi:[1,0]
	v_rcp_f32_e32 v196, v196
	v_rcp_f32_e32 v197, v197
	v_rcp_f32_e32 v198, v198
	v_rcp_f32_e32 v199, v199
	v_pk_mul_f32 v[188:189], v[188:189], v[196:197]
	v_pk_mul_f32 v[190:191], v[190:191], v[198:199]
	v_pk_mul_f32 v[188:189], v[188:189], v[192:193]
	v_pk_mul_f32 v[190:191], v[190:191], v[194:195]
	v_cvt_pk_bf16_f32 v122, v188, v189
	v_cvt_pk_bf16_f32 v123, v190, v191
	ds_read_b128 v[110:113], v109 offset:656
	v_pk_fma_f32 v[188:189], v[72:73], v[84:85], v[88:89]
	v_pk_fma_f32 v[190:191], v[74:75], v[86:87], v[90:91]
	v_pk_fma_f32 v[192:193], v[64:65], v[100:101], v[104:105]
	v_pk_fma_f32 v[194:195], v[66:67], v[102:103], v[106:107]
	v_cndmask_b32_e64 v114, v72, v114, s[10:11]
	v_cndmask_b32_e64 v115, v73, v115, s[10:11]
	v_cndmask_b32_e64 v116, v74, v116, s[10:11]
	v_cndmask_b32_e64 v117, v75, v117, s[10:11]
	v_cndmask_b32_e64 v68, v64, v68, s[10:11]
	v_cndmask_b32_e64 v69, v65, v69, s[10:11]
	v_cndmask_b32_e64 v70, v66, v70, s[10:11]
	v_cndmask_b32_e64 v71, v67, v71, s[10:11]
	v_fmac_f32_dpp v188, v114, v76 row_ror:2 row_mask:0xf bank_mask:0xf
	v_fmac_f32_dpp v189, v115, v77 row_ror:2 row_mask:0xf bank_mask:0xf
	v_fmac_f32_dpp v190, v116, v78 row_ror:2 row_mask:0xf bank_mask:0xf
	v_fmac_f32_dpp v191, v117, v79 row_ror:2 row_mask:0xf bank_mask:0xf
	v_fmac_f32_dpp v192, v68, v92 row_ror:2 row_mask:0xf bank_mask:0xf
	v_fmac_f32_dpp v193, v69, v93 row_ror:2 row_mask:0xf bank_mask:0xf
	v_fmac_f32_dpp v194, v70, v94 row_ror:2 row_mask:0xf bank_mask:0xf
	v_fmac_f32_dpp v195, v71, v95 row_ror:2 row_mask:0xf bank_mask:0xf
	v_cndmask_b32_e64 v114, v72, v114, s[8:9]
	v_cndmask_b32_e64 v115, v73, v115, s[8:9]
	v_cndmask_b32_e64 v116, v74, v116, s[8:9]
	v_cndmask_b32_e64 v117, v75, v117, s[8:9]
	v_cndmask_b32_e64 v68, v64, v68, s[8:9]
	v_cndmask_b32_e64 v69, v65, v69, s[8:9]
	v_cndmask_b32_e64 v70, v66, v70, s[8:9]
	v_cndmask_b32_e64 v71, v67, v71, s[8:9]
	v_fmac_f32_dpp v188, v114, v80 row_ror:1 row_mask:0xf bank_mask:0xf
	v_fmac_f32_dpp v189, v115, v81 row_ror:1 row_mask:0xf bank_mask:0xf
	v_fmac_f32_dpp v190, v116, v82 row_ror:1 row_mask:0xf bank_mask:0xf
	v_fmac_f32_dpp v191, v117, v83 row_ror:1 row_mask:0xf bank_mask:0xf
	v_fmac_f32_dpp v192, v68, v96 row_ror:1 row_mask:0xf bank_mask:0xf
	v_fmac_f32_dpp v193, v69, v97 row_ror:1 row_mask:0xf bank_mask:0xf
	v_fmac_f32_dpp v194, v70, v98 row_ror:1 row_mask:0xf bank_mask:0xf
	v_fmac_f32_dpp v195, v71, v99 row_ror:1 row_mask:0xf bank_mask:0xf
	v_pk_mul_f32 v[196:197], v[188:189], v[216:217] op_sel_hi:[1,0]
	v_pk_mul_f32 v[198:199], v[190:191], v[216:217] op_sel_hi:[1,0]
	v_exp_f32_e32 v196, v196
	v_exp_f32_e32 v197, v197
	v_exp_f32_e32 v198, v198
	v_exp_f32_e32 v199, v199
	v_pk_add_f32 v[196:197], v[196:197], v[214:215] op_sel_hi:[1,0]
	v_pk_add_f32 v[198:199], v[198:199], v[214:215] op_sel_hi:[1,0]
	v_rcp_f32_e32 v196, v196
	v_rcp_f32_e32 v197, v197
	v_rcp_f32_e32 v198, v198
	v_rcp_f32_e32 v199, v199
	v_pk_mul_f32 v[188:189], v[188:189], v[196:197]
	v_pk_mul_f32 v[190:191], v[190:191], v[198:199]
	v_pk_mul_f32 v[188:189], v[188:189], v[192:193]
	v_pk_mul_f32 v[190:191], v[190:191], v[194:195]
	v_cvt_pk_bf16_f32 v114, v188, v189
	v_cvt_pk_bf16_f32 v115, v190, v191
	s_waitcnt lgkmcnt(0)
	s_cmp_lg_u64 s[6:7], 0
	s_cselect_b32 s98, s0, s36
	s_cselect_b32 s99, s1, s34
	v_lshrrev_b32_e32 v196, 6, v222
	s_lshl_b32 s98, s98, 8
	s_add_i32 s98, s98, s58
	s_lshl_b32 s99, s99, 7
	s_add_i32 s99, s99, s53
	s_lshl_b32 s99, s99, 2
	v_and_b32_e32 v197, 63, v222
	v_add_u32_e32 v198, s98, v197
	v_lshlrev_b32_e32 v198, 2, v198
	v_lshrrev_b32_e32 v199, 3, v197
	v_and_b32_e32 v197, 7, v197
	v_readfirstlane_b32 s98, v196
	v_lshrrev_b32_e32 v196, 2, v199
	v_and_b32_e32 v199, 3, v199
	v_cmp_eq_u32_e64 s[100:101], 3, v199
	v_mul_u32_u24_e32 v199, 0xb000, v199
	v_add_u32_e32 v199, 0x21000, v199
	v_mov_b32_e32 v188, 0xb000
	v_cndmask_b32_e64 v199, v199, v188, s[100:101]
	v_mul_u32_u24_e32 v196, 0x5800, v196
	v_add3_u32 v199, v199, v196, s99
	v_lshl_add_u32 v199, v197, 4, v199
	s_lshl_b32 s100, s98, 9
	s_add_i32 m0, s100, 0x20040
	s_nop 0
	global_load_lds_dword v198, s[4:5]
	v_add_u32_e32 v198, 0x100, v198
	s_add_i32 m0, s100, 0x20140
	s_nop 0
	global_load_lds_dword v198, s[4:5]
	s_lshl_b32 s100, s98, 10
	s_add_i32 m0, s100, 0x21040
	s_mov_b32 exec_lo, 0x00ffffff
	s_mov_b32 exec_hi, 0x00ffffff
	global_load_lds_dwordx4 v199, s[82:83]
	s_mov_b32 exec_lo, 0xff000000
	s_mov_b32 exec_hi, 0xff000000
	global_load_lds_dwordx4 v199, s[84:85]
	s_mov_b64 exec, -1
	s_nop 4
	v_pk_fma_f32 v[188:189], v[60:61], v[134:135], v[130:131]
	v_pk_fma_f32 v[190:191], v[62:63], v[136:137], v[132:133]
	v_pk_fma_f32 v[192:193], v[56:57], v[204:205], v[208:209]
	v_pk_fma_f32 v[194:195], v[58:59], v[206:207], v[210:211]
	v_fmac_f32_dpp v188, v60, v142 row_shr:1 row_mask:0xf bank_mask:0xf
	v_fmac_f32_dpp v189, v61, v143 row_shr:1 row_mask:0xf bank_mask:0xf
	v_fmac_f32_dpp v190, v62, v144 row_shr:1 row_mask:0xf bank_mask:0xf
	v_fmac_f32_dpp v191, v63, v145 row_shr:1 row_mask:0xf bank_mask:0xf
	v_fmac_f32_dpp v192, v56, v110 row_shr:1 row_mask:0xf bank_mask:0xf
	v_fmac_f32_dpp v193, v57, v111 row_shr:1 row_mask:0xf bank_mask:0xf
	v_fmac_f32_dpp v194, v58, v112 row_shr:1 row_mask:0xf bank_mask:0xf
	v_fmac_f32_dpp v195, v59, v113 row_shr:1 row_mask:0xf bank_mask:0xf
	v_fmac_f32_dpp v188, v60, v154 row_shr:2 row_mask:0xf bank_mask:0xf
	v_fmac_f32_dpp v189, v61, v155 row_shr:2 row_mask:0xf bank_mask:0xf
	v_fmac_f32_dpp v190, v62, v156 row_shr:2 row_mask:0xf bank_mask:0xf
	v_fmac_f32_dpp v191, v63, v157 row_shr:2 row_mask:0xf bank_mask:0xf
	v_fmac_f32_dpp v192, v56, v118 row_shr:2 row_mask:0xf bank_mask:0xf
	v_fmac_f32_dpp v193, v57, v119 row_shr:2 row_mask:0xf bank_mask:0xf
	v_fmac_f32_dpp v194, v58, v120 row_shr:2 row_mask:0xf bank_mask:0xf
	v_fmac_f32_dpp v195, v59, v121 row_shr:2 row_mask:0xf bank_mask:0xf
	v_pk_mul_f32 v[196:197], v[188:189], v[216:217] op_sel_hi:[1,0]
	v_pk_mul_f32 v[198:199], v[190:191], v[216:217] op_sel_hi:[1,0]
	v_exp_f32_e32 v196, v196
	v_exp_f32_e32 v197, v197
	v_exp_f32_e32 v198, v198
	v_exp_f32_e32 v199, v199
	v_pk_add_f32 v[196:197], v[196:197], v[214:215] op_sel_hi:[1,0]
	v_pk_add_f32 v[198:199], v[198:199], v[214:215] op_sel_hi:[1,0]
	v_rcp_f32_e32 v196, v196
	v_rcp_f32_e32 v197, v197
	v_rcp_f32_e32 v198, v198
	v_rcp_f32_e32 v199, v199
	v_pk_mul_f32 v[188:189], v[188:189], v[196:197]
	v_pk_mul_f32 v[190:191], v[190:191], v[198:199]
	v_pk_mul_f32 v[188:189], v[188:189], v[192:193]
	v_pk_mul_f32 v[190:191], v[190:191], v[194:195]
	v_cvt_pk_bf16_f32 v202, v188, v189
	v_cvt_pk_bf16_f32 v203, v190, v191
	s_mov_b64 exec, vcc
	global_store_dwordx4 v215, v[200:203], s[96:97] nt
	s_mov_b64 exec, -1
	v_pk_fma_f32 v[188:189], v[52:53], v[134:135], v[130:131]
	v_pk_fma_f32 v[190:191], v[54:55], v[136:137], v[132:133]
	v_pk_fma_f32 v[192:193], v[44:45], v[204:205], v[208:209]
	v_pk_fma_f32 v[194:195], v[46:47], v[206:207], v[210:211]
	v_cndmask_b32_e64 v60, v52, v60, s[10:11]
	v_cndmask_b32_e64 v61, v53, v61, s[10:11]
	v_cndmask_b32_e64 v62, v54, v62, s[10:11]
	v_cndmask_b32_e64 v63, v55, v63, s[10:11]
	v_cndmask_b32_e64 v56, v44, v56, s[10:11]
	v_cndmask_b32_e64 v57, v45, v57, s[10:11]
	v_cndmask_b32_e64 v58, v46, v58, s[10:11]
	v_cndmask_b32_e64 v59, v47, v59, s[10:11]
	v_fmac_f32_dpp v188, v60, v154 row_ror:2 row_mask:0xf bank_mask:0xf
	v_fmac_f32_dpp v189, v61, v155 row_ror:2 row_mask:0xf bank_mask:0xf
	v_fmac_f32_dpp v190, v62, v156 row_ror:2 row_mask:0xf bank_mask:0xf
	v_fmac_f32_dpp v191, v63, v157 row_ror:2 row_mask:0xf bank_mask:0xf
	v_fmac_f32_dpp v192, v56, v118 row_ror:2 row_mask:0xf bank_mask:0xf
	v_fmac_f32_dpp v193, v57, v119 row_ror:2 row_mask:0xf bank_mask:0xf
	v_fmac_f32_dpp v194, v58, v120 row_ror:2 row_mask:0xf bank_mask:0xf
	v_fmac_f32_dpp v195, v59, v121 row_ror:2 row_mask:0xf bank_mask:0xf
	v_cndmask_b32_e64 v60, v52, v60, s[8:9]
	v_cndmask_b32_e64 v61, v53, v61, s[8:9]
	v_cndmask_b32_e64 v62, v54, v62, s[8:9]
	v_cndmask_b32_e64 v63, v55, v63, s[8:9]
	v_cndmask_b32_e64 v56, v44, v56, s[8:9]
	v_cndmask_b32_e64 v57, v45, v57, s[8:9]
	v_cndmask_b32_e64 v58, v46, v58, s[8:9]
	v_cndmask_b32_e64 v59, v47, v59, s[8:9]
	v_fmac_f32_dpp v188, v60, v142 row_ror:1 row_mask:0xf bank_mask:0xf
	v_fmac_f32_dpp v189, v61, v143 row_ror:1 row_mask:0xf bank_mask:0xf
	v_fmac_f32_dpp v190, v62, v144 row_ror:1 row_mask:0xf bank_mask:0xf
	v_fmac_f32_dpp v191, v63, v145 row_ror:1 row_mask:0xf bank_mask:0xf
	v_fmac_f32_dpp v192, v56, v110 row_ror:1 row_mask:0xf bank_mask:0xf
	v_fmac_f32_dpp v193, v57, v111 row_ror:1 row_mask:0xf bank_mask:0xf
	v_fmac_f32_dpp v194, v58, v112 row_ror:1 row_mask:0xf bank_mask:0xf
	v_fmac_f32_dpp v195, v59, v113 row_ror:1 row_mask:0xf bank_mask:0xf
	v_pk_mul_f32 v[196:197], v[188:189], v[216:217] op_sel_hi:[1,0]
	v_pk_mul_f32 v[198:199], v[190:191], v[216:217] op_sel_hi:[1,0]
	v_exp_f32_e32 v196, v196
	v_exp_f32_e32 v197, v197
	v_exp_f32_e32 v198, v198
	v_exp_f32_e32 v199, v199
	v_pk_add_f32 v[196:197], v[196:197], v[214:215] op_sel_hi:[1,0]
	v_pk_add_f32 v[198:199], v[198:199], v[214:215] op_sel_hi:[1,0]
	v_rcp_f32_e32 v196, v196
	v_rcp_f32_e32 v197, v197
	v_rcp_f32_e32 v198, v198
	v_rcp_f32_e32 v199, v199
	v_pk_mul_f32 v[188:189], v[188:189], v[196:197]
	v_pk_mul_f32 v[190:191], v[190:191], v[198:199]
	v_pk_mul_f32 v[188:189], v[188:189], v[192:193]
	v_pk_mul_f32 v[190:191], v[190:191], v[194:195]
	v_cvt_pk_bf16_f32 v160, v188, v189
	v_cvt_pk_bf16_f32 v161, v190, v191
	v_add_u32_e32 v213, 0x2c000, v215
	global_store_dwordx4 v213, v[158:161], s[96:97] nt
	v_pk_fma_f32 v[188:189], v[48:49], v[134:135], v[130:131]
	v_pk_fma_f32 v[190:191], v[50:51], v[136:137], v[132:133]
	v_pk_fma_f32 v[192:193], v[36:37], v[204:205], v[208:209]
	v_pk_fma_f32 v[194:195], v[38:39], v[206:207], v[210:211]
	v_cndmask_b32_e64 v52, v48, v52, s[10:11]
	v_cndmask_b32_e64 v53, v49, v53, s[10:11]
	v_cndmask_b32_e64 v54, v50, v54, s[10:11]
	v_cndmask_b32_e64 v55, v51, v55, s[10:11]
	v_cndmask_b32_e64 v44, v36, v44, s[10:11]
	v_cndmask_b32_e64 v45, v37, v45, s[10:11]
	v_cndmask_b32_e64 v46, v38, v46, s[10:11]
	v_cndmask_b32_e64 v47, v39, v47, s[10:11]
	v_fmac_f32_dpp v188, v52, v154 row_ror:2 row_mask:0xf bank_mask:0xf
	v_fmac_f32_dpp v189, v53, v155 row_ror:2 row_mask:0xf bank_mask:0xf
	v_fmac_f32_dpp v190, v54, v156 row_ror:2 row_mask:0xf bank_mask:0xf
	v_fmac_f32_dpp v191, v55, v157 row_ror:2 row_mask:0xf bank_mask:0xf
	v_fmac_f32_dpp v192, v44, v118 row_ror:2 row_mask:0xf bank_mask:0xf
	v_fmac_f32_dpp v193, v45, v119 row_ror:2 row_mask:0xf bank_mask:0xf
	v_fmac_f32_dpp v194, v46, v120 row_ror:2 row_mask:0xf bank_mask:0xf
	v_fmac_f32_dpp v195, v47, v121 row_ror:2 row_mask:0xf bank_mask:0xf
	v_cndmask_b32_e64 v52, v48, v52, s[8:9]
	v_cndmask_b32_e64 v53, v49, v53, s[8:9]
	v_cndmask_b32_e64 v54, v50, v54, s[8:9]
	v_cndmask_b32_e64 v55, v51, v55, s[8:9]
	v_cndmask_b32_e64 v44, v36, v44, s[8:9]
	v_cndmask_b32_e64 v45, v37, v45, s[8:9]
	v_cndmask_b32_e64 v46, v38, v46, s[8:9]
	v_cndmask_b32_e64 v47, v39, v47, s[8:9]
	v_fmac_f32_dpp v188, v52, v142 row_ror:1 row_mask:0xf bank_mask:0xf
	v_fmac_f32_dpp v189, v53, v143 row_ror:1 row_mask:0xf bank_mask:0xf
	v_fmac_f32_dpp v190, v54, v144 row_ror:1 row_mask:0xf bank_mask:0xf
	v_fmac_f32_dpp v191, v55, v145 row_ror:1 row_mask:0xf bank_mask:0xf
	v_fmac_f32_dpp v192, v44, v110 row_ror:1 row_mask:0xf bank_mask:0xf
	v_fmac_f32_dpp v193, v45, v111 row_ror:1 row_mask:0xf bank_mask:0xf
	v_fmac_f32_dpp v194, v46, v112 row_ror:1 row_mask:0xf bank_mask:0xf
	v_fmac_f32_dpp v195, v47, v113 row_ror:1 row_mask:0xf bank_mask:0xf
	v_pk_mul_f32 v[196:197], v[188:189], v[216:217] op_sel_hi:[1,0]
	v_pk_mul_f32 v[198:199], v[190:191], v[216:217] op_sel_hi:[1,0]
	v_exp_f32_e32 v196, v196
	v_exp_f32_e32 v197, v197
	v_exp_f32_e32 v198, v198
	v_exp_f32_e32 v199, v199
	v_pk_add_f32 v[196:197], v[196:197], v[214:215] op_sel_hi:[1,0]
	v_pk_add_f32 v[198:199], v[198:199], v[214:215] op_sel_hi:[1,0]
	v_rcp_f32_e32 v196, v196
	v_rcp_f32_e32 v197, v197
	v_rcp_f32_e32 v198, v198
	v_rcp_f32_e32 v199, v199
	v_pk_mul_f32 v[188:189], v[188:189], v[196:197]
	v_pk_mul_f32 v[190:191], v[190:191], v[198:199]
	v_pk_mul_f32 v[188:189], v[188:189], v[192:193]
	v_pk_mul_f32 v[190:191], v[190:191], v[194:195]
	v_cvt_pk_bf16_f32 v152, v188, v189
	v_cvt_pk_bf16_f32 v153, v190, v191
	v_add_u32_e32 v213, 0x58000, v215
	global_store_dwordx4 v213, v[150:153], s[96:97] nt
	v_pk_fma_f32 v[188:189], v[40:41], v[134:135], v[130:131]
	v_pk_fma_f32 v[190:191], v[42:43], v[136:137], v[132:133]
	v_pk_fma_f32 v[192:193], v[32:33], v[204:205], v[208:209]
	v_pk_fma_f32 v[194:195], v[34:35], v[206:207], v[210:211]
	v_cndmask_b32_e64 v48, v40, v48, s[10:11]
	v_cndmask_b32_e64 v49, v41, v49, s[10:11]
	v_cndmask_b32_e64 v50, v42, v50, s[10:11]
	v_cndmask_b32_e64 v51, v43, v51, s[10:11]
	v_cndmask_b32_e64 v36, v32, v36, s[10:11]
	v_cndmask_b32_e64 v37, v33, v37, s[10:11]
	v_cndmask_b32_e64 v38, v34, v38, s[10:11]
	v_cndmask_b32_e64 v39, v35, v39, s[10:11]
	v_fmac_f32_dpp v188, v48, v154 row_ror:2 row_mask:0xf bank_mask:0xf
	v_fmac_f32_dpp v189, v49, v155 row_ror:2 row_mask:0xf bank_mask:0xf
	v_fmac_f32_dpp v190, v50, v156 row_ror:2 row_mask:0xf bank_mask:0xf
	v_fmac_f32_dpp v191, v51, v157 row_ror:2 row_mask:0xf bank_mask:0xf
	v_fmac_f32_dpp v192, v36, v118 row_ror:2 row_mask:0xf bank_mask:0xf
	v_fmac_f32_dpp v193, v37, v119 row_ror:2 row_mask:0xf bank_mask:0xf
	v_fmac_f32_dpp v194, v38, v120 row_ror:2 row_mask:0xf bank_mask:0xf
	v_fmac_f32_dpp v195, v39, v121 row_ror:2 row_mask:0xf bank_mask:0xf
	v_cndmask_b32_e64 v48, v40, v48, s[8:9]
	v_cndmask_b32_e64 v49, v41, v49, s[8:9]
	v_cndmask_b32_e64 v50, v42, v50, s[8:9]
	v_cndmask_b32_e64 v51, v43, v51, s[8:9]
	v_cndmask_b32_e64 v36, v32, v36, s[8:9]
	v_cndmask_b32_e64 v37, v33, v37, s[8:9]
	v_cndmask_b32_e64 v38, v34, v38, s[8:9]
	v_cndmask_b32_e64 v39, v35, v39, s[8:9]
	v_fmac_f32_dpp v188, v48, v142 row_ror:1 row_mask:0xf bank_mask:0xf
	v_fmac_f32_dpp v189, v49, v143 row_ror:1 row_mask:0xf bank_mask:0xf
	v_fmac_f32_dpp v190, v50, v144 row_ror:1 row_mask:0xf bank_mask:0xf
	v_fmac_f32_dpp v191, v51, v145 row_ror:1 row_mask:0xf bank_mask:0xf
	v_fmac_f32_dpp v192, v36, v110 row_ror:1 row_mask:0xf bank_mask:0xf
	v_fmac_f32_dpp v193, v37, v111 row_ror:1 row_mask:0xf bank_mask:0xf
	v_fmac_f32_dpp v194, v38, v112 row_ror:1 row_mask:0xf bank_mask:0xf
	v_fmac_f32_dpp v195, v39, v113 row_ror:1 row_mask:0xf bank_mask:0xf
	v_pk_mul_f32 v[196:197], v[188:189], v[216:217] op_sel_hi:[1,0]
	v_pk_mul_f32 v[198:199], v[190:191], v[216:217] op_sel_hi:[1,0]
	v_exp_f32_e32 v196, v196
	v_exp_f32_e32 v197, v197
	v_exp_f32_e32 v198, v198
	v_exp_f32_e32 v199, v199
	v_pk_add_f32 v[196:197], v[196:197], v[214:215] op_sel_hi:[1,0]
	v_pk_add_f32 v[198:199], v[198:199], v[214:215] op_sel_hi:[1,0]
	v_rcp_f32_e32 v196, v196
	v_rcp_f32_e32 v197, v197
	v_rcp_f32_e32 v198, v198
	v_rcp_f32_e32 v199, v199
	v_pk_mul_f32 v[188:189], v[188:189], v[196:197]
	v_pk_mul_f32 v[190:191], v[190:191], v[198:199]
	v_pk_mul_f32 v[188:189], v[188:189], v[192:193]
	v_pk_mul_f32 v[190:191], v[190:191], v[194:195]
	v_cvt_pk_bf16_f32 v148, v188, v189
	v_cvt_pk_bf16_f32 v149, v190, v191
	v_add_u32_e32 v213, 0x84000, v215
	global_store_dwordx4 v213, v[146:149], s[96:97] nt
	v_pk_fma_f32 v[188:189], v[28:29], v[134:135], v[130:131]
	v_pk_fma_f32 v[190:191], v[30:31], v[136:137], v[132:133]
	v_pk_fma_f32 v[192:193], v[16:17], v[204:205], v[208:209]
	v_pk_fma_f32 v[194:195], v[18:19], v[206:207], v[210:211]
	v_cndmask_b32_e64 v40, v28, v40, s[10:11]
	v_cndmask_b32_e64 v41, v29, v41, s[10:11]
	v_cndmask_b32_e64 v42, v30, v42, s[10:11]
	v_cndmask_b32_e64 v43, v31, v43, s[10:11]
	v_cndmask_b32_e64 v32, v16, v32, s[10:11]
	v_cndmask_b32_e64 v33, v17, v33, s[10:11]
	v_cndmask_b32_e64 v34, v18, v34, s[10:11]
	v_cndmask_b32_e64 v35, v19, v35, s[10:11]
	v_fmac_f32_dpp v188, v40, v154 row_ror:2 row_mask:0xf bank_mask:0xf
	v_fmac_f32_dpp v189, v41, v155 row_ror:2 row_mask:0xf bank_mask:0xf
	v_fmac_f32_dpp v190, v42, v156 row_ror:2 row_mask:0xf bank_mask:0xf
	v_fmac_f32_dpp v191, v43, v157 row_ror:2 row_mask:0xf bank_mask:0xf
	v_fmac_f32_dpp v192, v32, v118 row_ror:2 row_mask:0xf bank_mask:0xf
	v_fmac_f32_dpp v193, v33, v119 row_ror:2 row_mask:0xf bank_mask:0xf
	v_fmac_f32_dpp v194, v34, v120 row_ror:2 row_mask:0xf bank_mask:0xf
	v_fmac_f32_dpp v195, v35, v121 row_ror:2 row_mask:0xf bank_mask:0xf
	v_cndmask_b32_e64 v40, v28, v40, s[8:9]
	v_cndmask_b32_e64 v41, v29, v41, s[8:9]
	v_cndmask_b32_e64 v42, v30, v42, s[8:9]
	v_cndmask_b32_e64 v43, v31, v43, s[8:9]
	v_cndmask_b32_e64 v32, v16, v32, s[8:9]
	v_cndmask_b32_e64 v33, v17, v33, s[8:9]
	v_cndmask_b32_e64 v34, v18, v34, s[8:9]
	v_cndmask_b32_e64 v35, v19, v35, s[8:9]
	v_fmac_f32_dpp v188, v40, v142 row_ror:1 row_mask:0xf bank_mask:0xf
	v_fmac_f32_dpp v189, v41, v143 row_ror:1 row_mask:0xf bank_mask:0xf
	v_fmac_f32_dpp v190, v42, v144 row_ror:1 row_mask:0xf bank_mask:0xf
	v_fmac_f32_dpp v191, v43, v145 row_ror:1 row_mask:0xf bank_mask:0xf
	v_fmac_f32_dpp v192, v32, v110 row_ror:1 row_mask:0xf bank_mask:0xf
	v_fmac_f32_dpp v193, v33, v111 row_ror:1 row_mask:0xf bank_mask:0xf
	v_fmac_f32_dpp v194, v34, v112 row_ror:1 row_mask:0xf bank_mask:0xf
	v_fmac_f32_dpp v195, v35, v113 row_ror:1 row_mask:0xf bank_mask:0xf
	v_pk_mul_f32 v[196:197], v[188:189], v[216:217] op_sel_hi:[1,0]
	v_pk_mul_f32 v[198:199], v[190:191], v[216:217] op_sel_hi:[1,0]
	v_exp_f32_e32 v196, v196
	v_exp_f32_e32 v197, v197
	v_exp_f32_e32 v198, v198
	v_exp_f32_e32 v199, v199
	v_pk_add_f32 v[196:197], v[196:197], v[214:215] op_sel_hi:[1,0]
	v_pk_add_f32 v[198:199], v[198:199], v[214:215] op_sel_hi:[1,0]
	v_rcp_f32_e32 v196, v196
	v_rcp_f32_e32 v197, v197
	v_rcp_f32_e32 v198, v198
	v_rcp_f32_e32 v199, v199
	v_pk_mul_f32 v[188:189], v[188:189], v[196:197]
	v_pk_mul_f32 v[190:191], v[190:191], v[198:199]
	v_pk_mul_f32 v[188:189], v[188:189], v[192:193]
	v_pk_mul_f32 v[190:191], v[190:191], v[194:195]
	v_cvt_pk_bf16_f32 v140, v188, v189
	v_cvt_pk_bf16_f32 v141, v190, v191
	v_add_u32_e32 v213, 0xb0000, v215
	global_store_dwordx4 v213, v[138:141], s[96:97] nt
	v_pk_fma_f32 v[188:189], v[24:25], v[134:135], v[130:131]
	v_pk_fma_f32 v[190:191], v[26:27], v[136:137], v[132:133]
	v_pk_fma_f32 v[192:193], v[12:13], v[204:205], v[208:209]
	v_pk_fma_f32 v[194:195], v[14:15], v[206:207], v[210:211]
	v_cndmask_b32_e64 v28, v24, v28, s[10:11]
	v_cndmask_b32_e64 v29, v25, v29, s[10:11]
	v_cndmask_b32_e64 v30, v26, v30, s[10:11]
	v_cndmask_b32_e64 v31, v27, v31, s[10:11]
	v_cndmask_b32_e64 v16, v12, v16, s[10:11]
	v_cndmask_b32_e64 v17, v13, v17, s[10:11]
	v_cndmask_b32_e64 v18, v14, v18, s[10:11]
	v_cndmask_b32_e64 v19, v15, v19, s[10:11]
	v_fmac_f32_dpp v188, v28, v154 row_ror:2 row_mask:0xf bank_mask:0xf
	v_fmac_f32_dpp v189, v29, v155 row_ror:2 row_mask:0xf bank_mask:0xf
	v_fmac_f32_dpp v190, v30, v156 row_ror:2 row_mask:0xf bank_mask:0xf
	v_fmac_f32_dpp v191, v31, v157 row_ror:2 row_mask:0xf bank_mask:0xf
	v_fmac_f32_dpp v192, v16, v118 row_ror:2 row_mask:0xf bank_mask:0xf
	v_fmac_f32_dpp v193, v17, v119 row_ror:2 row_mask:0xf bank_mask:0xf
	v_fmac_f32_dpp v194, v18, v120 row_ror:2 row_mask:0xf bank_mask:0xf
	v_fmac_f32_dpp v195, v19, v121 row_ror:2 row_mask:0xf bank_mask:0xf
	v_cndmask_b32_e64 v28, v24, v28, s[8:9]
	v_cndmask_b32_e64 v29, v25, v29, s[8:9]
	v_cndmask_b32_e64 v30, v26, v30, s[8:9]
	v_cndmask_b32_e64 v31, v27, v31, s[8:9]
	v_cndmask_b32_e64 v16, v12, v16, s[8:9]
	v_cndmask_b32_e64 v17, v13, v17, s[8:9]
	v_cndmask_b32_e64 v18, v14, v18, s[8:9]
	v_cndmask_b32_e64 v19, v15, v19, s[8:9]
	v_fmac_f32_dpp v188, v28, v142 row_ror:1 row_mask:0xf bank_mask:0xf
	v_fmac_f32_dpp v189, v29, v143 row_ror:1 row_mask:0xf bank_mask:0xf
	v_fmac_f32_dpp v190, v30, v144 row_ror:1 row_mask:0xf bank_mask:0xf
	v_fmac_f32_dpp v191, v31, v145 row_ror:1 row_mask:0xf bank_mask:0xf
	v_fmac_f32_dpp v192, v16, v110 row_ror:1 row_mask:0xf bank_mask:0xf
	v_fmac_f32_dpp v193, v17, v111 row_ror:1 row_mask:0xf bank_mask:0xf
	v_fmac_f32_dpp v194, v18, v112 row_ror:1 row_mask:0xf bank_mask:0xf
	v_fmac_f32_dpp v195, v19, v113 row_ror:1 row_mask:0xf bank_mask:0xf
	v_pk_mul_f32 v[196:197], v[188:189], v[216:217] op_sel_hi:[1,0]
	v_pk_mul_f32 v[198:199], v[190:191], v[216:217] op_sel_hi:[1,0]
	v_exp_f32_e32 v196, v196
	v_exp_f32_e32 v197, v197
	v_exp_f32_e32 v198, v198
	v_exp_f32_e32 v199, v199
	v_pk_add_f32 v[196:197], v[196:197], v[214:215] op_sel_hi:[1,0]
	v_pk_add_f32 v[198:199], v[198:199], v[214:215] op_sel_hi:[1,0]
	v_rcp_f32_e32 v196, v196
	v_rcp_f32_e32 v197, v197
	v_rcp_f32_e32 v198, v198
	v_rcp_f32_e32 v199, v199
	v_pk_mul_f32 v[188:189], v[188:189], v[196:197]
	v_pk_mul_f32 v[190:191], v[190:191], v[198:199]
	v_pk_mul_f32 v[188:189], v[188:189], v[192:193]
	v_pk_mul_f32 v[190:191], v[190:191], v[194:195]
	v_cvt_pk_bf16_f32 v128, v188, v189
	v_cvt_pk_bf16_f32 v129, v190, v191
	v_add_u32_e32 v213, 0xdc000, v215
	global_store_dwordx4 v213, v[126:129], s[96:97] nt
	v_pk_fma_f32 v[188:189], v[20:21], v[134:135], v[130:131]
	v_pk_fma_f32 v[190:191], v[22:23], v[136:137], v[132:133]
	v_pk_fma_f32 v[192:193], v[8:9], v[204:205], v[208:209]
	v_pk_fma_f32 v[194:195], v[10:11], v[206:207], v[210:211]
	v_cndmask_b32_e64 v24, v20, v24, s[10:11]
	v_cndmask_b32_e64 v25, v21, v25, s[10:11]
	v_cndmask_b32_e64 v26, v22, v26, s[10:11]
	v_cndmask_b32_e64 v27, v23, v27, s[10:11]
	v_cndmask_b32_e64 v12, v8, v12, s[10:11]
	v_cndmask_b32_e64 v13, v9, v13, s[10:11]
	v_cndmask_b32_e64 v14, v10, v14, s[10:11]
	v_cndmask_b32_e64 v15, v11, v15, s[10:11]
	v_fmac_f32_dpp v188, v24, v154 row_ror:2 row_mask:0xf bank_mask:0xf
	v_fmac_f32_dpp v189, v25, v155 row_ror:2 row_mask:0xf bank_mask:0xf
	v_fmac_f32_dpp v190, v26, v156 row_ror:2 row_mask:0xf bank_mask:0xf
	v_fmac_f32_dpp v191, v27, v157 row_ror:2 row_mask:0xf bank_mask:0xf
	v_fmac_f32_dpp v192, v12, v118 row_ror:2 row_mask:0xf bank_mask:0xf
	v_fmac_f32_dpp v193, v13, v119 row_ror:2 row_mask:0xf bank_mask:0xf
	v_fmac_f32_dpp v194, v14, v120 row_ror:2 row_mask:0xf bank_mask:0xf
	v_fmac_f32_dpp v195, v15, v121 row_ror:2 row_mask:0xf bank_mask:0xf
	v_cndmask_b32_e64 v24, v20, v24, s[8:9]
	v_cndmask_b32_e64 v25, v21, v25, s[8:9]
	v_cndmask_b32_e64 v26, v22, v26, s[8:9]
	v_cndmask_b32_e64 v27, v23, v27, s[8:9]
	v_cndmask_b32_e64 v12, v8, v12, s[8:9]
	v_cndmask_b32_e64 v13, v9, v13, s[8:9]
	v_cndmask_b32_e64 v14, v10, v14, s[8:9]
	v_cndmask_b32_e64 v15, v11, v15, s[8:9]
	v_fmac_f32_dpp v188, v24, v142 row_ror:1 row_mask:0xf bank_mask:0xf
	v_fmac_f32_dpp v189, v25, v143 row_ror:1 row_mask:0xf bank_mask:0xf
	v_fmac_f32_dpp v190, v26, v144 row_ror:1 row_mask:0xf bank_mask:0xf
	v_fmac_f32_dpp v191, v27, v145 row_ror:1 row_mask:0xf bank_mask:0xf
	v_fmac_f32_dpp v192, v12, v110 row_ror:1 row_mask:0xf bank_mask:0xf
	v_fmac_f32_dpp v193, v13, v111 row_ror:1 row_mask:0xf bank_mask:0xf
	v_fmac_f32_dpp v194, v14, v112 row_ror:1 row_mask:0xf bank_mask:0xf
	v_fmac_f32_dpp v195, v15, v113 row_ror:1 row_mask:0xf bank_mask:0xf
	v_pk_mul_f32 v[196:197], v[188:189], v[216:217] op_sel_hi:[1,0]
	v_pk_mul_f32 v[198:199], v[190:191], v[216:217] op_sel_hi:[1,0]
	v_exp_f32_e32 v196, v196
	v_exp_f32_e32 v197, v197
	v_exp_f32_e32 v198, v198
	v_exp_f32_e32 v199, v199
	v_pk_add_f32 v[196:197], v[196:197], v[214:215] op_sel_hi:[1,0]
	v_pk_add_f32 v[198:199], v[198:199], v[214:215] op_sel_hi:[1,0]
	v_rcp_f32_e32 v196, v196
	v_rcp_f32_e32 v197, v197
	v_rcp_f32_e32 v198, v198
	v_rcp_f32_e32 v199, v199
	v_pk_mul_f32 v[188:189], v[188:189], v[196:197]
	v_pk_mul_f32 v[190:191], v[190:191], v[198:199]
	v_pk_mul_f32 v[188:189], v[188:189], v[192:193]
	v_pk_mul_f32 v[190:191], v[190:191], v[194:195]
	v_cvt_pk_bf16_f32 v124, v188, v189
	v_cvt_pk_bf16_f32 v125, v190, v191
	v_add_u32_e32 v213, 0x108000, v215
	global_store_dwordx4 v213, v[122:125], s[96:97] nt
	v_pk_fma_f32 v[188:189], v[4:5], v[134:135], v[130:131]
	v_pk_fma_f32 v[190:191], v[6:7], v[136:137], v[132:133]
	v_pk_fma_f32 v[192:193], v[0:1], v[204:205], v[208:209]
	v_pk_fma_f32 v[194:195], v[2:3], v[206:207], v[210:211]
	v_cndmask_b32_e64 v20, v4, v20, s[10:11]
	v_cndmask_b32_e64 v21, v5, v21, s[10:11]
	v_cndmask_b32_e64 v22, v6, v22, s[10:11]
	v_cndmask_b32_e64 v23, v7, v23, s[10:11]
	v_cndmask_b32_e64 v8, v0, v8, s[10:11]
	v_cndmask_b32_e64 v9, v1, v9, s[10:11]
	v_cndmask_b32_e64 v10, v2, v10, s[10:11]
	v_cndmask_b32_e64 v11, v3, v11, s[10:11]
	v_fmac_f32_dpp v188, v20, v154 row_ror:2 row_mask:0xf bank_mask:0xf
	v_fmac_f32_dpp v189, v21, v155 row_ror:2 row_mask:0xf bank_mask:0xf
	v_fmac_f32_dpp v190, v22, v156 row_ror:2 row_mask:0xf bank_mask:0xf
	v_fmac_f32_dpp v191, v23, v157 row_ror:2 row_mask:0xf bank_mask:0xf
	v_fmac_f32_dpp v192, v8, v118 row_ror:2 row_mask:0xf bank_mask:0xf
	v_fmac_f32_dpp v193, v9, v119 row_ror:2 row_mask:0xf bank_mask:0xf
	v_fmac_f32_dpp v194, v10, v120 row_ror:2 row_mask:0xf bank_mask:0xf
	v_fmac_f32_dpp v195, v11, v121 row_ror:2 row_mask:0xf bank_mask:0xf
	v_cndmask_b32_e64 v20, v4, v20, s[8:9]
	v_cndmask_b32_e64 v21, v5, v21, s[8:9]
	v_cndmask_b32_e64 v22, v6, v22, s[8:9]
	v_cndmask_b32_e64 v23, v7, v23, s[8:9]
	v_cndmask_b32_e64 v8, v0, v8, s[8:9]
	v_cndmask_b32_e64 v9, v1, v9, s[8:9]
	v_cndmask_b32_e64 v10, v2, v10, s[8:9]
	v_cndmask_b32_e64 v11, v3, v11, s[8:9]
	v_fmac_f32_dpp v188, v20, v142 row_ror:1 row_mask:0xf bank_mask:0xf
	v_fmac_f32_dpp v189, v21, v143 row_ror:1 row_mask:0xf bank_mask:0xf
	v_fmac_f32_dpp v190, v22, v144 row_ror:1 row_mask:0xf bank_mask:0xf
	v_fmac_f32_dpp v191, v23, v145 row_ror:1 row_mask:0xf bank_mask:0xf
	v_fmac_f32_dpp v192, v8, v110 row_ror:1 row_mask:0xf bank_mask:0xf
	v_fmac_f32_dpp v193, v9, v111 row_ror:1 row_mask:0xf bank_mask:0xf
	v_fmac_f32_dpp v194, v10, v112 row_ror:1 row_mask:0xf bank_mask:0xf
	v_fmac_f32_dpp v195, v11, v113 row_ror:1 row_mask:0xf bank_mask:0xf
	v_pk_mul_f32 v[196:197], v[188:189], v[216:217] op_sel_hi:[1,0]
	v_pk_mul_f32 v[198:199], v[190:191], v[216:217] op_sel_hi:[1,0]
	v_exp_f32_e32 v196, v196
	v_exp_f32_e32 v197, v197
	v_exp_f32_e32 v198, v198
	v_exp_f32_e32 v199, v199
	v_pk_add_f32 v[196:197], v[196:197], v[214:215] op_sel_hi:[1,0]
	v_pk_add_f32 v[198:199], v[198:199], v[214:215] op_sel_hi:[1,0]
	v_rcp_f32_e32 v196, v196
	v_rcp_f32_e32 v197, v197
	v_rcp_f32_e32 v198, v198
	v_rcp_f32_e32 v199, v199
	v_pk_mul_f32 v[188:189], v[188:189], v[196:197]
	v_pk_mul_f32 v[190:191], v[190:191], v[198:199]
	v_pk_mul_f32 v[188:189], v[188:189], v[192:193]
	v_pk_mul_f32 v[190:191], v[190:191], v[194:195]
	v_cvt_pk_bf16_f32 v116, v188, v189
	v_cvt_pk_bf16_f32 v117, v190, v191
	v_add_u32_e32 v213, 0x134000, v215
	global_store_dwordx4 v213, v[114:117], s[96:97] nt
	s_branch .LBB0_836

	.amdhsa_kernel _Z14fwd_megakernel6Params
		.amdhsa_group_segment_fixed_size 8192
		.amdhsa_private_segment_fixed_size 0
		.amdhsa_kernarg_size 408
		.amdhsa_user_sgpr_count 2
		.amdhsa_user_sgpr_dispatch_ptr 0
		.amdhsa_user_sgpr_queue_ptr 0
		.amdhsa_user_sgpr_kernarg_segment_ptr 1
		.amdhsa_user_sgpr_dispatch_id 0
		.amdhsa_user_sgpr_kernarg_preload_length 0
		.amdhsa_user_sgpr_kernarg_preload_offset 0
		.amdhsa_user_sgpr_private_segment_size 0
		.amdhsa_uses_dynamic_stack 0
		.amdhsa_enable_private_segment 0
		.amdhsa_system_sgpr_workgroup_id_x 1
		.amdhsa_system_sgpr_workgroup_id_y 0
		.amdhsa_system_sgpr_workgroup_id_z 0
		.amdhsa_system_sgpr_workgroup_info 0
		.amdhsa_system_vgpr_workitem_id 2
		.amdhsa_next_free_vgpr 256
		.amdhsa_next_free_sgpr 102
		.amdhsa_accum_offset 256
		.amdhsa_reserve_vcc 1
		.amdhsa_float_round_mode_32 0
		.amdhsa_float_round_mode_16_64 0
		.amdhsa_float_denorm_mode_32 3
		.amdhsa_float_denorm_mode_16_64 3
		.amdhsa_dx10_clamp 1
		.amdhsa_ieee_mode 1
		.amdhsa_fp16_overflow 0
		.amdhsa_tg_split 0
		.amdhsa_exception_fp_ieee_invalid_op 0
		.amdhsa_exception_fp_denorm_src 0
		.amdhsa_exception_fp_ieee_div_zero 0
		.amdhsa_exception_fp_ieee_overflow 0
		.amdhsa_exception_fp_ieee_underflow 0
		.amdhsa_exception_fp_ieee_inexact 0
		.amdhsa_exception_int_div_zero 0
	.end_amdhsa_kernel

amdhsa.kernels:
  - .agpr_count:     0
    .args:
      - .offset:         0
        .size:           152
        .value_kind:     by_value
      - .offset:         152
        .size:           4
        .value_kind:     hidden_block_count_x
      - .offset:         156
        .size:           4
        .value_kind:     hidden_block_count_y
      - .offset:         160
        .size:           4
        .value_kind:     hidden_block_count_z
      - .offset:         164
        .size:           2
        .value_kind:     hidden_group_size_x
      - .offset:         166
        .size:           2
        .value_kind:     hidden_group_size_y
      - .offset:         168
        .size:           2
        .value_kind:     hidden_group_size_z
      - .offset:         170
        .size:           2
        .value_kind:     hidden_remainder_x
      - .offset:         172
        .size:           2
        .value_kind:     hidden_remainder_y
      - .offset:         174
        .size:           2
        .value_kind:     hidden_remainder_z
      - .offset:         192
        .size:           8
        .value_kind:     hidden_global_offset_x
      - .offset:         200
        .size:           8
        .value_kind:     hidden_global_offset_y
      - .offset:         208
        .size:           8
        .value_kind:     hidden_global_offset_z
      - .offset:         216
        .size:           2
        .value_kind:     hidden_grid_dims
      - .offset:         240
        .size:           8
        .value_kind:     hidden_multigrid_sync_arg
      - .offset:         272
        .size:           4
        .value_kind:     hidden_dynamic_lds_size
    .group_segment_fixed_size: 8192
    .kernarg_segment_align: 8
    .kernarg_segment_size: 408
    .language:       OpenCL C
    .language_version:
      - 2
      - 0
    .max_flat_workgroup_size: 512
    .name:           _Z14fwd_megakernel6Params
    .private_segment_fixed_size: 0
    .sgpr_count:     108
    .sgpr_spill_count: 19
    .symbol:         _Z14fwd_megakernel6Params.kd
    .uniform_work_group_size: 1
    .uses_dynamic_stack: false
    .vgpr_count:     256
    .vgpr_spill_count: 0
    .wavefront_size: 64
